# xor16/xor32 reductions via permlane swaps in attention unit and GEMM epilogues (30+10 sites)
# speedup vs baseline: 1.0135x; 1.0053x over previous
; template <int MODE> ...
;     ...
;     lrun += __shfl_xor(lrun, 16); lrun += __shfl_xor(lrun, 32);
;     const float inv = lrun > 0.f ? 1.f / lrun : 0.f;
; #pragma unroll
;     for (int dt = 0; dt < 4; ++dt) o[dt] *= inv;
; __device__ __forceinline__ void attn_unit(int bg, int pb, bool build, const bf16* Q, const bf16* KV, const bf16* KCN, const bf16* VCT, const float* GATES, const float* rel_bias, bf16* A, unsigned char* lds) {
;     ...
;         attn_stream<0>(KV + 2 * KV_ELEMS + (size_t)bg * 2048 * 64, KV + 3 * KV_ELEMS + (size_t)bg * 64 * 2048, qf0, qf1, t, p0, pb, selm, bias, cfar, o, qi, q4, tid, lds);
; #pragma unroll
;         for (int dt = 0; dt < 4; ++dt) acc[dt] += o[dt] * g1;
;     }
;     {
;         f32x4 o[4];
;         attn_stream<1>(KV + 4 * KV_ELEMS + (size_t)bg * 2048 * 64, KV + 5 * KV_ELEMS + (size_t)bg * 64 * 2048, qf0, qf1, t, p0, pb, 0u, bias, cfar, o, qi, q4, tid, lds);
; #pragma unroll
;         for (int dt = 0; dt < 4; ++dt) acc[dt] += o[dt] * g2;
;     }
; #pragma unroll
;     for (int dt = 0; dt < 4; ++dt) {
;         u32x2 pk; pk.x = cvtpk(acc[dt][0], acc[dt][1]); pk.y = cvtpk(acc[dt][2], acc[dt][3]);
;         *(u32x2*)(A + tok * 1024 + head * 64 + dt * 16 + q4 * 4) = pk;
;     }
.LBB0_232:
	v_mov_b32_e32 v0, v146
	v_mov_b32_e32 v126, v146
	s_nop 1
	v_permlane16_swap_b32_e32 v0, v126
	s_lshl_b32 s38, s74, 1
	s_add_i32 s2, s2, s72
	s_mov_b32 s97, 0x30000
	s_mov_b32 s83, 0x40000
	s_waitcnt lgkmcnt(0)
	v_add_f32_e32 v126, v126, v0
	v_mov_b32_e32 v130, v126
	s_nop 1
	v_permlane32_swap_b32_e32 v130, v126
	s_mov_b32 s85, 0x28000
	s_mov_b32 s6, s69
	s_mov_b32 s67, 0x18000
	s_mov_b32 s69, 0x8000
	s_waitcnt lgkmcnt(0)
	v_pk_add_f32 v[18:19], v[126:127], v[130:131]
	s_nop 0
	v_div_scale_f32 v0, s[0:1], v19, v19, 1.0
	v_rcp_f32_e32 v20, v0
	v_div_scale_f32 v21, vcc, 1.0, v19, 1.0
	v_fma_f32 v22, -v0, v20, 1.0
	v_fmac_f32_e32 v20, v22, v20
	v_mul_f32_e32 v22, v21, v20
	v_fma_f32 v23, -v0, v22, v21
	v_fmac_f32_e32 v22, v23, v20
	v_fma_f32 v0, -v0, v22, v21
	v_div_fmas_f32 v0, v0, v20, v22
	v_div_fixup_f32 v0, v0, v19, 1.0
	v_cmp_lt_f32_e32 vcc, 0, v19
	s_nop 1
	v_cndmask_b32_e32 v0, 0, v0, vcc
	v_pk_mul_f32 v[20:21], v[54:55], v[0:1] op_sel_hi:[1,0]
	v_pk_mul_f32 v[22:23], v[56:57], v[0:1] op_sel_hi:[1,0]
	v_pk_mul_f32 v[20:21], v[122:123], v[20:21] op_sel:[1,0]
	v_pk_mul_f32 v[22:23], v[122:123], v[22:23] op_sel:[1,0]
	v_pk_mul_f32 v[24:25], v[50:51], v[0:1] op_sel_hi:[1,0]
	v_pk_mul_f32 v[50:51], v[52:53], v[0:1] op_sel_hi:[1,0]
	v_pk_mul_f32 v[42:43], v[42:43], v[0:1] op_sel_hi:[1,0]
	v_pk_fma_f32 v[20:21], v[122:123], v[38:39], v[20:21] op_sel_hi:[0,1,1]
	v_pk_fma_f32 v[22:23], v[122:123], v[40:41], v[22:23] op_sel_hi:[0,1,1]
	v_pk_mul_f32 v[38:39], v[44:45], v[0:1] op_sel_hi:[1,0]
	v_pk_mul_f32 v[40:41], v[46:47], v[0:1] op_sel_hi:[1,0]
	v_pk_mul_f32 v[44:45], v[48:49], v[0:1] op_sel_hi:[1,0]
	v_div_scale_f32 v0, s[0:1], v18, v18, 1.0
	v_rcp_f32_e32 v19, v0
	v_pk_mul_f32 v[46:47], v[122:123], v[50:51] op_sel:[1,0]
	v_pk_mul_f32 v[24:25], v[122:123], v[24:25] op_sel:[1,0]
	v_readlane_b32 s0, v255, 40
	v_pk_fma_f32 v[24:25], v[122:123], v[34:35], v[24:25] op_sel_hi:[0,1,1]
	v_pk_fma_f32 v[34:35], v[122:123], v[36:37], v[46:47] op_sel_hi:[0,1,1]
	v_pk_mul_f32 v[36:37], v[122:123], v[38:39] op_sel:[1,0]
	v_pk_mul_f32 v[38:39], v[122:123], v[42:43] op_sel:[1,0]
	v_pk_fma_f32 v[32:33], v[122:123], v[32:33], v[36:37] op_sel_hi:[0,1,1]
	v_pk_mul_f32 v[36:37], v[122:123], v[44:45] op_sel:[1,0]
	v_pk_fma_f32 v[30:31], v[122:123], v[30:31], v[38:39] op_sel_hi:[0,1,1]
	v_pk_fma_f32 v[28:29], v[122:123], v[28:29], v[36:37] op_sel_hi:[0,1,1]
	v_fma_f32 v36, -v0, v19, 1.0
	v_fmac_f32_e32 v19, v36, v19
	v_div_scale_f32 v36, vcc, 1.0, v18, 1.0
	v_pk_mul_f32 v[38:39], v[122:123], v[40:41] op_sel:[1,0]
	v_mul_f32_e32 v37, v36, v19
	v_pk_fma_f32 v[26:27], v[122:123], v[26:27], v[38:39] op_sel_hi:[0,1,1]
	v_fma_f32 v38, -v0, v37, v36
	v_fmac_f32_e32 v37, v38, v19
	v_fma_f32 v0, -v0, v37, v36
	v_div_fmas_f32 v0, v0, v19, v37
	v_div_fixup_f32 v0, v0, v18, 1.0
	v_cmp_lt_f32_e32 vcc, 0, v18
	v_readlane_b32 s1, v255, 41
	s_nop 0
	v_cndmask_b32_e32 v0, 0, v0, vcc
	v_pk_mul_f32 v[2:3], v[2:3], v[0:1] op_sel_hi:[1,0]
	v_pk_mul_f32 v[4:5], v[4:5], v[0:1] op_sel_hi:[1,0]
	v_pk_mul_f32 v[6:7], v[6:7], v[0:1] op_sel_hi:[1,0]
	v_pk_mul_f32 v[8:9], v[8:9], v[0:1] op_sel_hi:[1,0]
	v_pk_mul_f32 v[10:11], v[10:11], v[0:1] op_sel_hi:[1,0]
	v_pk_mul_f32 v[12:13], v[12:13], v[0:1] op_sel_hi:[1,0]
	v_pk_mul_f32 v[14:15], v[14:15], v[0:1] op_sel_hi:[1,0]
	v_pk_mul_f32 v[16:17], v[16:17], v[0:1] op_sel_hi:[1,0]
	v_mov_b32_e32 v0, v124
	v_lshl_add_u64 v[18:19], v[128:129], 1, s[0:1]
	v_pk_fma_f32 v[4:5], v[0:1], v[4:5], v[28:29] op_sel_hi:[0,1,1]
	v_pk_fma_f32 v[2:3], v[0:1], v[2:3], v[26:27] op_sel_hi:[0,1,1]
	v_pk_fma_f32 v[8:9], v[0:1], v[8:9], v[32:33] op_sel_hi:[0,1,1]
	v_pk_fma_f32 v[6:7], v[0:1], v[6:7], v[30:31] op_sel_hi:[0,1,1]
	v_pk_fma_f32 v[12:13], v[0:1], v[12:13], v[34:35] op_sel_hi:[0,1,1]
	v_pk_fma_f32 v[10:11], v[0:1], v[10:11], v[24:25] op_sel_hi:[0,1,1]
	v_pk_fma_f32 v[16:17], v[0:1], v[16:17], v[22:23] op_sel_hi:[0,1,1]
	v_pk_fma_f32 v[14:15], v[0:1], v[14:15], v[20:21] op_sel_hi:[0,1,1]
	v_lshl_add_u64 v[18:19], v[18:19], 0, s[38:39]
	v_lshlrev_b32_e32 v0, 1, v138
	v_lshl_add_u64 v[18:19], v[18:19], 0, v[0:1]
	v_cvt_pk_bf16_f32 v2, v2, v3
	v_cvt_pk_bf16_f32 v3, v4, v5
	global_store_dwordx2 v[18:19], v[2:3], off
	v_cvt_pk_bf16_f32 v2, v6, v7
	v_cvt_pk_bf16_f32 v3, v8, v9
	v_readlane_b32 s0, v254, 26
	global_store_dwordx2 v[18:19], v[2:3], off offset:32
	v_cvt_pk_bf16_f32 v2, v10, v11
	v_cvt_pk_bf16_f32 v3, v12, v13
	s_add_i32 s33, s33, s0
	global_store_dwordx2 v[18:19], v[2:3], off offset:64
	v_cvt_pk_bf16_f32 v2, v14, v15
	v_cvt_pk_bf16_f32 v3, v16, v17
	s_cmpk_gt_i32 s2, 0x3ff
	s_movk_i32 s38, 0x6000
	global_store_dwordx2 v[18:19], v[2:3], off offset:96
	s_cbranch_scc1 .LBB0_648

; __device__ __forceinline__ void attn_unit(int bg, int pb, bool build, const bf16* Q, const bf16* KV, const bf16* KCN, const bf16* VCT, const float* GATES, const float* rel_bias, bf16* A, unsigned char* lds) {
;     ...
;         mx = fmaxf(mx, __shfl_xor(mx, 16)); mx = fmaxf(mx, __shfl_xor(mx, 32));
;         float sum = 0.f;
; #pragma unroll
;         for (int st = 0; st < 4; ++st)
; #pragma unroll
;             for (int ph = 0; ph < 2; ++ph)
; #pragma unroll
;                 for (int j = 0; j < 4; ++j) { const float p = pc[st][ph][j] > -1e29f ? __builtin_amdgcn_exp2f(pc[st][ph][j] - mx) : 0.f; pc[st][ph][j] = p; sum += p; }
;         sum += __shfl_xor(sum, 16); sum += __shfl_xor(sum, 32);
.Lcmp_done:
.LBB0_322:
	v_and_b32_e32 v3, 64, v226
	v_xor_b32_e32 v2, 16, v226
	v_add_u32_e32 v3, 64, v3
	v_cmp_lt_i32_e32 vcc, v2, v3
	v_xor_b32_e32 v5, 32, v226
	v_max_f32_e32 v4, v8, v8
	v_cndmask_b32_e32 v2, v226, v2, vcc
	v_lshlrev_b32_e32 v136, 2, v2
	v_mov_b32_e32 v2, v4
	s_nop 1
	v_permlane16_swap_b32_e32 v2, v4
	v_cmp_lt_i32_e32 vcc, v5, v3
	s_lshl_b32 s10, s12, 5
	s_add_i32 s10, s10, s75
	v_cndmask_b32_e32 v3, v226, v5, vcc
	s_waitcnt lgkmcnt(0)
	v_max_f32_e32 v2, v2, v2
	v_max_f32_e32 v2, v4, v2
	v_lshlrev_b32_e32 v137, 2, v3
	v_mov_b32_e32 v3, v2
	s_nop 1
	v_permlane32_swap_b32_e32 v3, v2
	v_cmp_lt_f32_e32 vcc, s95, v6
	v_lshlrev_b32_e32 v138, 2, v59
	s_waitcnt lgkmcnt(0)
	v_max_f32_e32 v3, v3, v3
	v_max_f32_e32 v8, v2, v3
	v_sub_f32_e32 v2, v15, v8
	v_exp_f32_e32 v52, v2
	v_sub_f32_e32 v2, v26, v8
	v_exp_f32_e32 v62, v2
	v_sub_f32_e32 v2, v27, v8
	v_exp_f32_e32 v63, v2
	v_sub_f32_e32 v2, v28, v8
	v_exp_f32_e32 v64, v2
	v_sub_f32_e32 v2, v29, v8
	v_exp_f32_e32 v65, v2
	v_sub_f32_e32 v2, v30, v8
	v_exp_f32_e32 v66, v2
	v_sub_f32_e32 v2, v31, v8
	v_exp_f32_e32 v67, v2
	v_sub_f32_e32 v2, v33, v8
	v_exp_f32_e32 v56, v2
	v_sub_f32_e32 v2, v32, v8
	v_exp_f32_e32 v57, v2
	v_sub_f32_e32 v2, v34, v8
	v_exp_f32_e32 v54, v2
	v_sub_f32_e32 v2, v35, v8
	v_exp_f32_e32 v55, v2
	v_sub_f32_e32 v2, v36, v8
	v_exp_f32_e32 v68, v2
	v_sub_f32_e32 v2, v37, v8
	v_exp_f32_e32 v69, v2
	v_sub_f32_e32 v2, v38, v8
	v_exp_f32_e32 v70, v2
	v_sub_f32_e32 v2, v39, v8
	v_sub_f32_e32 v3, v14, v8
	v_exp_f32_e32 v71, v2
	v_sub_f32_e32 v2, v6, v8
	v_exp_f32_e32 v53, v3
	v_exp_f32_e32 v2, v2
	v_sub_f32_e32 v3, v7, v8
	v_exp_f32_e32 v3, v3
	v_sub_f32_e32 v5, v47, v8
	v_cndmask_b32_e32 v11, 0, v2, vcc
	v_cmp_lt_f32_e32 vcc, s95, v7
	v_sub_f32_e32 v2, v12, v8
	v_exp_f32_e32 v2, v2
	v_cndmask_b32_e32 v10, 0, v3, vcc
	v_sub_f32_e32 v3, v16, v8
	v_exp_f32_e32 v3, v3
	v_cmp_lt_f32_e32 vcc, s95, v12
	v_exp_f32_e32 v6, v5
	v_sub_f32_e32 v7, v49, v8
	v_cndmask_b32_e32 v13, 0, v2, vcc
	v_cmp_lt_f32_e32 vcc, s95, v16
	v_sub_f32_e32 v2, v17, v8
	v_exp_f32_e32 v2, v2
	v_cndmask_b32_e32 v12, 0, v3, vcc
	v_sub_f32_e32 v3, v40, v8
	v_exp_f32_e32 v3, v3
	v_cmp_lt_f32_e32 vcc, s95, v17
	v_exp_f32_e32 v9, v7
	s_nop 0
	v_cndmask_b32_e32 v17, 0, v2, vcc
	v_cmp_lt_f32_e32 vcc, s95, v40
	v_sub_f32_e32 v2, v41, v8
	v_exp_f32_e32 v2, v2
	v_cndmask_b32_e32 v16, 0, v3, vcc
	v_sub_f32_e32 v3, v42, v8
	v_exp_f32_e32 v3, v3
	v_cmp_lt_f32_e32 vcc, s95, v41
	s_nop 1
	v_cndmask_b32_e32 v43, 0, v2, vcc
	v_cmp_lt_f32_e32 vcc, s95, v42
	v_sub_f32_e32 v2, v44, v8
	v_exp_f32_e32 v2, v2
	v_cndmask_b32_e32 v42, 0, v3, vcc
	v_sub_f32_e32 v3, v45, v8
	v_exp_f32_e32 v4, v3
	v_cmp_lt_f32_e32 vcc, s95, v44
	s_nop 1
	v_cndmask_b32_e32 v3, 0, v2, vcc
	v_cmp_lt_f32_e32 vcc, s95, v45
	s_nop 1
	v_cndmask_b32_e32 v2, 0, v4, vcc
	v_sub_f32_e32 v4, v46, v8
	v_exp_f32_e32 v4, v4
	v_cmp_lt_f32_e32 vcc, s95, v46
	s_nop 1
	v_cndmask_b32_e32 v5, 0, v4, vcc
	v_cmp_lt_f32_e32 vcc, s95, v47
	s_nop 1
	v_cndmask_b32_e32 v4, 0, v6, vcc
	v_sub_f32_e32 v6, v48, v8
	v_exp_f32_e32 v6, v6
	v_cmp_lt_f32_e32 vcc, s95, v48
	s_nop 1
	v_cndmask_b32_e32 v7, 0, v6, vcc
	v_cmp_lt_f32_e32 vcc, s95, v49
	s_nop 1
	v_cndmask_b32_e32 v6, 0, v9, vcc
	v_sub_f32_e32 v9, v50, v8
	v_exp_f32_e32 v9, v9
	v_sub_f32_e32 v8, v51, v8
	v_exp_f32_e32 v8, v8
	v_cmp_lt_f32_e32 vcc, s95, v50
	s_nop 1
	v_cndmask_b32_e32 v9, 0, v9, vcc
	v_cmp_lt_f32_e32 vcc, s95, v51
	s_nop 1
	v_cndmask_b32_e32 v8, 0, v8, vcc
	v_cmp_lt_f32_e32 vcc, s95, v39
	s_nop 1
	v_cndmask_b32_e32 v51, 0, v71, vcc
	v_cmp_lt_f32_e32 vcc, s95, v38
	s_nop 1
	v_cndmask_b32_e32 v50, 0, v70, vcc
	v_cmp_lt_f32_e32 vcc, s95, v37
	s_nop 1
	v_cndmask_b32_e32 v49, 0, v69, vcc
	v_cmp_lt_f32_e32 vcc, s95, v36
	s_nop 1
	v_cndmask_b32_e32 v48, 0, v68, vcc
	v_cmp_lt_f32_e32 vcc, s95, v35
	s_nop 1
	v_cndmask_b32_e32 v55, 0, v55, vcc
	v_cmp_lt_f32_e32 vcc, s95, v34
	v_or_b32_e32 v34, s10, v58
	v_readlane_b32 s10, v254, 50
	v_cndmask_b32_e32 v54, 0, v54, vcc
	v_cmp_lt_f32_e32 vcc, s95, v32
	v_lshl_or_b32 v34, v34, 7, v138
	v_add_u32_e32 v38, 0, v34
	v_cndmask_b32_e32 v57, 0, v57, vcc
	v_cmp_lt_f32_e32 vcc, s95, v33
	s_nop 1
	v_cndmask_b32_e32 v56, 0, v56, vcc
	v_cmp_lt_f32_e32 vcc, s95, v31
	s_nop 1
	v_cndmask_b32_e32 v31, 0, v67, vcc
	v_cmp_lt_f32_e32 vcc, s95, v30
	s_nop 1
	v_cndmask_b32_e32 v30, 0, v66, vcc
	v_cmp_lt_f32_e32 vcc, s95, v29
	s_nop 1
	v_cndmask_b32_e32 v29, 0, v65, vcc
	v_cmp_lt_f32_e32 vcc, s95, v28
	s_nop 1
	v_cndmask_b32_e32 v28, 0, v64, vcc
	v_cmp_lt_f32_e32 vcc, s95, v27
	s_nop 1
	v_cndmask_b32_e32 v27, 0, v63, vcc
	v_cmp_lt_f32_e32 vcc, s95, v26
	s_nop 1
	v_cndmask_b32_e32 v26, 0, v62, vcc
	v_cmp_lt_f32_e32 vcc, s95, v15
	s_nop 1
	v_cndmask_b32_e32 v32, 0, v52, vcc
	v_cmp_lt_f32_e32 vcc, s95, v14
	v_add_f32_e32 v33, 0, v32
	v_add_u32_e32 v52, 0x800, v38
	v_cndmask_b32_e32 v15, 0, v53, vcc
	v_add_f32_e32 v14, v15, v33
	v_add_f32_e32 v14, v26, v14
	v_add_f32_e32 v14, v27, v14
	v_add_f32_e32 v14, v28, v14
	v_add_f32_e32 v14, v29, v14
	v_add_f32_e32 v14, v30, v14
	v_add_f32_e32 v14, v31, v14
	v_add_f32_e32 v14, v56, v14
	v_add_f32_e32 v14, v57, v14
	v_add_f32_e32 v14, v54, v14
	v_add_f32_e32 v14, v55, v14
	v_add_f32_e32 v14, v48, v14
	v_add_f32_e32 v14, v49, v14
	v_add_f32_e32 v14, v50, v14
	v_add_f32_e32 v14, v51, v14
	v_add_f32_e32 v14, v10, v14
	v_add_f32_e32 v14, v11, v14
	v_add_f32_e32 v14, v12, v14
	v_add_f32_e32 v14, v13, v14
	v_add_f32_e32 v14, v16, v14
	v_add_f32_e32 v14, v17, v14
	v_add_f32_e32 v14, v42, v14
	v_add_f32_e32 v14, v43, v14
	v_add_f32_e32 v14, v2, v14
	v_add_f32_e32 v14, v3, v14
	v_add_f32_e32 v14, v4, v14
	v_add_f32_e32 v14, v5, v14
	v_add_f32_e32 v14, v6, v14
	v_add_f32_e32 v14, v7, v14
	v_add_f32_e32 v14, v8, v14
	v_add_f32_e32 v14, v9, v14
	v_mov_b32_e32 v33, v14
	s_nop 1
	v_permlane16_swap_b32_e32 v33, v14
	v_add_u32_e32 v53, s10, v0
	s_waitcnt lgkmcnt(0)
; __device__ __forceinline__ bf16x8 pack_p(const float* a, const float* b) { u32x4 w; w.x = cvtpk(a[0], a[1]); w.y = cvtpk(a[2], a[3]); w.z = cvtpk(b[0], b[1]); w.w = cvtpk(b[2], b[3]); return __builtin_bit_cast(bf16x8, w); }
; __device__ __forceinline__ bf16x8 ldv(const bf16* p) { const s16x4 lo = *(const s16x4*)p, hi = *(const s16x4*)(p + 16); return __builtin_shufflevector(lo, hi, 0, 1, 2, 3, 4, 5, 6, 7); }
; __device__ __forceinline__ void attn_unit(int bg, int pb, bool build, const bf16* Q, const bf16* KV, const bf16* KCN, const bf16* VCT, const float* GATES, const float* rel_bias, bf16* A, unsigned char* lds) {
;     ...
;         sum += __shfl_xor(sum, 16); sum += __shfl_xor(sum, 32);
;         const float inv = sum > 0.f ? 1.f / sum : 0.f;
;         f32x4 oc[4];
; #pragma unroll
;         for (int dt = 0; dt < 4; ++dt) oc[dt] = (f32x4){0.f, 0.f, 0.f, 0.f};
;         const int prow = (hl * 32 + half * 16 + qi) * 32;
; #pragma unroll
;         for (int st = 0; st < 4; ++st) {
; #pragma unroll
;             for (int ph = 0; ph < 2; ++ph) {
; #pragma unroll
;                 for (int j = 0; j < 4; ++j) pc[st][ph][j] *= inv;
;                 const int jj = st * 8 + ph * 4 + q4;
;                 impA[prow + jj] = pc[st][ph][0] + pc[st][ph][1] + pc[st][ph][2] + 0.5f * pc[st][ph][3];
;                 impB[prow + jj] = 0.5f * pc[st][ph][3];
;             }
;             if (st < nst) {
;                 const bf16x8 pf = pack_p(pc[st][0], pc[st][1]);
; #pragma unroll
;                 for (int dt = 0; dt < 4; ++dt) { const bf16x8 vf = ldv((const bf16*)(lds + AL_CV + (dt * 16 + qi) * CVP) + st * 32 + q4 * 4); oc[dt] = __builtin_amdgcn_mfma_f32_16x16x32_bf16(vf, pf, oc[dt], 0, 0, 0); }
;             }
;         }
; #pragma unroll
;         for (int dt = 0; dt < 4; ++dt) acc[dt] = oc[dt] * g0;
	v_add_f32_e32 v14, v14, v33
	v_mov_b32_e32 v33, v14
	s_nop 1
	v_permlane32_swap_b32_e32 v33, v14
	s_waitcnt lgkmcnt(0)
	v_add_f32_e32 v0, v14, v33
	v_div_scale_f32 v14, s[10:11], v0, v0, 1.0
	v_rcp_f32_e32 v33, v14
	s_movk_i32 s10, 0x110
	v_mad_u32_u24 v44, v58, s10, v53
	v_fma_f32 v34, -v14, v33, 1.0
	v_fmac_f32_e32 v33, v34, v33
	v_div_scale_f32 v34, vcc, 1.0, v0, 1.0
	v_mul_f32_e32 v35, v34, v33
	v_fma_f32 v36, -v14, v35, v34
	v_fmac_f32_e32 v35, v36, v33
	v_fma_f32 v14, -v14, v35, v34
	v_div_fmas_f32 v14, v14, v33, v35
	v_div_fixup_f32 v14, v14, v0, 1.0
	v_cmp_lt_f32_e32 vcc, 0, v0
	s_nop 1
	v_cndmask_b32_e32 v14, 0, v14, vcc
	v_mov_b32_e32 v33, v14
	v_pk_mul_f32 v[34:35], v[26:27], v[14:15] op_sel_hi:[1,0]
	v_pk_mul_f32 v[32:33], v[14:15], v[32:33]
	v_mul_f32_e32 v15, 0.5, v35
	v_pk_mul_f32 v[36:37], v[28:29], v[14:15] op_sel_hi:[1,0]
	v_add_f32_e32 v0, v32, v33
	v_pk_mul_f32 v[30:31], v[30:31], v[14:15] op_sel_hi:[1,0]
	v_add_f32_e32 v26, v36, v37
	v_add_f32_e32 v0, v34, v0
	v_add_f32_e32 v26, v30, v26
	v_fmac_f32_e32 v0, 0.5, v35
	v_fmac_f32_e32 v26, 0.5, v31
	v_mul_f32_e32 v27, 0.5, v31
	ds_write2_b32 v52, v0, v26 offset1:4
	v_add_u32_e32 v0, 0x4800, v38
	ds_write2_b32 v0, v15, v27 offset1:4
	v_add_u32_e32 v15, 0x1000, v44
	v_cvt_pk_bf16_f32 v38, v32, v33
	v_cvt_pk_bf16_f32 v41, v30, v31
	ds_read2_b64 v[30:33], v15 offset0:32 offset1:36
	v_add_u32_e32 v15, 0x2000, v44
	v_cvt_pk_bf16_f32 v39, v34, v35
	v_cvt_pk_bf16_f32 v40, v36, v37
	ds_read2_b64 v[34:37], v15 offset0:64 offset1:68
	v_add_u32_e32 v15, 0x3000, v44
	ds_read2_b64 v[26:29], v44 offset1:4
	ds_read2_b64 v[44:47], v15 offset0:96 offset1:100
	v_mul_u32_u24_e32 v15, 0x110, v58
	s_waitcnt lgkmcnt(1)
	v_mfma_f32_16x16x32_bf16 v[26:29], v[26:29], v[38:41], 0
	v_mul_f32_e64 v48, v48, v14
	v_mul_f32_e64 v49, v49, v14
	v_pk_mul_f32 v[50:51], v[50:51], v[14:15] op_sel_hi:[1,0]
	s_andn2_b64 vcc, exec, s[86:87]
	v_mfma_f32_16x16x32_bf16 v[30:33], v[30:33], v[38:41], 0
	v_mfma_f32_16x16x32_bf16 v[34:37], v[34:37], v[38:41], 0
	s_waitcnt lgkmcnt(0)
	v_mfma_f32_16x16x32_bf16 v[38:41], v[44:47], v[38:41], 0
	v_mul_f32_e64 v44, v56, v14
	v_mul_f32_e64 v45, v57, v14
	v_pk_mul_f32 v[46:47], v[54:55], v[14:15] op_sel_hi:[1,0]
	v_add_f32_e32 v54, v44, v45
	v_add_f32_e32 v56, v48, v49
	v_add_f32_e32 v54, v46, v54
	v_add_f32_e32 v56, v50, v56
	v_fmac_f32_e32 v54, 0.5, v47
	v_fmac_f32_e32 v56, 0.5, v51
	v_mul_f32_e32 v55, 0.5, v47
	v_mul_f32_e32 v57, 0.5, v51
	ds_write2_b32 v52, v54, v56 offset0:8 offset1:12
	ds_write2_b32 v0, v55, v57 offset0:8 offset1:12
	v_add_u32_e32 v56, v53, v15
	v_add_u32_e32 v55, 0x1000, v56
	v_add_u32_e32 v54, 0x2000, v56
	v_add_u32_e32 v53, 0x3000, v56
	s_cbranch_vccnz .LBB0_324
	v_cvt_pk_bf16_f32 v44, v44, v45
	v_cvt_pk_bf16_f32 v45, v46, v47
	v_cvt_pk_bf16_f32 v46, v48, v49
	v_cvt_pk_bf16_f32 v47, v50, v51
	ds_read2_b64 v[180:183], v56 offset0:8 offset1:12
	ds_read2_b64 v[184:187], v55 offset0:40 offset1:44
	ds_read2_b64 v[188:191], v54 offset0:72 offset1:76
	ds_read2_b64 v[192:195], v53 offset0:104 offset1:108
	s_waitcnt lgkmcnt(3)
	v_mfma_f32_16x16x32_bf16 v[26:29], v[180:183], v[44:47], v[26:29]
	s_waitcnt lgkmcnt(2)
	v_mfma_f32_16x16x32_bf16 v[30:33], v[184:187], v[44:47], v[30:33]
	s_waitcnt lgkmcnt(1)
	v_mfma_f32_16x16x32_bf16 v[34:37], v[188:191], v[44:47], v[34:37]
	s_waitcnt lgkmcnt(0)
	v_mfma_f32_16x16x32_bf16 v[38:41], v[192:195], v[44:47], v[38:41]

; #define AT_LOAD(s_, k_, v_) do { k_ = *(const u32x4*)(kg + (size_t)(s_) * 4096); v_ = *(const u32x4*)(vg + (s_) * 64); } while (0)
; template <int MODE> ...
;     ...
;     u32x4 ka, va, kb = {0u, 0u, 0u, 0u}, vb = {0u, 0u, 0u, 0u};
;     AT_LOAD(st_lo, ka, va);
;     if (st_lo + 1 <= st_hi) AT_LOAD(st_lo + 1, kb, vb);
;     ...
;     lrun += __shfl_xor(lrun, 16); lrun += __shfl_xor(lrun, 32);
.Lsel_exit_go:
	s_mov_b32 s0, 0
	v_writelane_b32 v255, s0, 61
	s_lshl_b32 s6, s12, 1
	v_readlane_b32 s0, v255, 47
	s_add_u32 s0, s0, s6
	v_readlane_b32 s1, v255, 48
	s_addc_u32 s1, s1, 0
	v_readlane_b32 s7, v255, 49
	s_add_u32 s10, s7, s6
	v_readlane_b32 s6, v255, 50
	s_addc_u32 s11, s6, 0
	s_addk_i32 s96, 0xfe01
	s_lshr_b32 s12, s96, 6
	s_and_b64 s[6:7], s[86:87], exec
	s_cselect_b32 s6, s12, 0
	s_waitcnt vmcnt(1)
	v_lshl_add_u64 v[2:3], s[0:1], 0, v[106:107]
	v_lshlrev_b32_e32 v4, 1, v116
	v_mov_b32_e32 v5, v1
	s_mov_b32 s7, s39
	v_lshl_add_u64 v[2:3], v[2:3], 0, v[4:5]
	s_waitcnt vmcnt(0)
	v_lshl_add_u64 v[6:7], s[10:11], 0, v[108:109]
	s_lshl_b64 s[12:13], s[6:7], 13
	v_lshl_add_u64 v[132:133], v[6:7], 0, v[4:5]
	v_lshl_add_u64 v[4:5], v[2:3], 0, s[12:13]
	s_lshl_b32 s10, s6, 6
	s_mov_b32 s11, s39
	v_lshl_add_u64 v[6:7], s[10:11], 1, v[132:133]
	global_load_dwordx4 v[58:61], v[4:5], off
	global_load_dwordx4 v[62:65], v[6:7], off
	v_mov_b32_e32 v4, v117
	v_mov_b32_e32 v127, v117
	s_nop 1
	v_permlane16_swap_b32_e32 v4, v127
	s_cmp_ge_u32 s6, s97
	s_waitcnt lgkmcnt(0)
	v_add_f32_e32 v127, v127, v4
	v_mov_b32_e32 v131, v127
	s_nop 1
	v_permlane32_swap_b32_e32 v131, v127
	s_cbranch_scc1 .LBB0_620
	s_add_i32 s0, s6, 1
	s_mov_b32 s1, s39
	s_lshl_b32 s14, s0, 7
	s_lshl_b64 s[0:1], s[0:1], 13
	s_mov_b32 s15, s39
	v_lshl_add_u64 v[2:3], v[2:3], 0, s[0:1]
	v_lshl_add_u64 v[4:5], v[132:133], 0, s[14:15]
	global_load_dwordx4 v[70:73], v[2:3], off
	global_load_dwordx4 v[66:69], v[4:5], off
	s_branch .LBB0_621

; __device__ __forceinline__ float sigm(float x) { return __builtin_amdgcn_rcpf(1.f + __expf(-x)); }
; __device__ __forceinline__ float gelu_tanh(float x) { return x * sigm(1.5957691216f * (x + 0.044715f * x * x * x)); }
; __device__ __forceinline__ u32x4 pack8(const float* v) { u32x4 w; w.x = cvtpk(v[0], v[1]); w.y = cvtpk(v[2], v[3]); w.z = cvtpk(v[4], v[5]); w.w = cvtpk(v[6], v[7]); return w; }
;     template <int KIND>
;     __device__ __forceinline__ void act_tile(const pg8::f32x4 (&acc)[2][2][4][2], const float (&rs)[2][4], unsigned char* w_, int row0, int colt, int statslot, int fq_) const {
;     ...
;         for (int ai = 0; ai < 2; ++ai)
; #pragma unroll
;             for (int m = 0; m < 4; ++m) {
;                 const int row = row0 + ai * 128 + m * 16;
;                 float s1 = 0.f, s2 = 0.f;
; #pragma unroll
;                 for (int bj = 0; bj < 2; ++bj) {
;                     float v[8];
; #pragma unroll
;                     for (int n = 0; n < 2; ++n)
; #pragma unroll
;                         for (int j = 0; j < 4; ++j) {
;                             const float a = acc[ai][bj][m][n][j] * rs[ai][m];
;                             const float r = KIND == 2 ? sigm(a) : gelu_tanh(a);
;                             v[n * 4 + j] = r;
;                             if (KIND == 1) { s1 += r; s2 += r * r; }
;                         }
;                     *(u32x4*)(base + (size_t)row * ldc + colt + bj * 128) = pack8(v);
;                 }
;                 if (KIND == 1) {
;                     s1 += __shfl_xor(s1, 16); s1 += __shfl_xor(s1, 32); s2 += __shfl_xor(s2, 16); s2 += __shfl_xor(s2, 32);
;     __device__ __forceinline__ void operator()(const pg8::f32x4 (&acc)[2][2][4][2], const pg8::Unit& u, int wr, int wc, int fr, int fq) const {
;     ...
;             else if (pn < 18) act_tile<1>(acc, rs, w_, row0, (pn - 14) * 256 + wc * 32 + fq_ * 8, (pn - 14) * 4 + wc, fq_);
.LBB0_871:
	s_andn2_b64 vcc, exec, s[0:1]
	s_cbranch_vccnz .LBB0_889
	s_waitcnt lgkmcnt(0)
	v_pk_mul_f32 v[138:139], v[126:127], v[164:165] op_sel_hi:[1,0]
	v_pk_mul_f32 v[142:143], v[128:129], v[164:165] op_sel_hi:[1,0]
	v_mul_f32_e32 v140, 0x3d372713, v138
	v_mul_f32_e32 v141, 0x3d372713, v139
	v_mul_f32_e32 v140, v138, v140
	v_mul_f32_e32 v141, v139, v141
	v_fma_f32 v140, v138, v140, v138
	v_fma_f32 v141, v139, v141, v139
	v_mul_f32_e32 v144, 0x3d372713, v142
	v_mul_f32_e32 v145, 0x3d372713, v143
	v_mul_f32_e32 v140, 0x3fcc422a, v140
	v_mul_f32_e32 v141, 0x3fcc422a, v141
	v_mul_f32_e32 v144, v142, v144
	v_mul_f32_e32 v145, v143, v145
	v_mul_f32_e32 v140, 0xbfb8aa3b, v140
	v_mul_f32_e32 v141, 0xbfb8aa3b, v141
	v_fma_f32 v144, v142, v144, v142
	v_fma_f32 v145, v143, v145, v143
	v_exp_f32_e32 v140, v140
	v_exp_f32_e32 v141, v141
	v_mul_f32_e32 v144, 0x3fcc422a, v144
	v_mul_f32_e32 v145, 0x3fcc422a, v145
	v_mul_f32_e32 v144, 0xbfb8aa3b, v144
	v_mul_f32_e32 v145, 0xbfb8aa3b, v145
	v_exp_f32_e32 v144, v144
	v_exp_f32_e32 v145, v145
	v_add_f32_e32 v140, 1.0, v140
	v_add_f32_e32 v141, 1.0, v141
	v_rcp_f32_e32 v140, v140
	v_rcp_f32_e32 v141, v141
	v_add_f32_e32 v144, 1.0, v144
	v_add_f32_e32 v145, 1.0, v145
	v_and_b32_e32 v131, 64, v226
	v_rcp_f32_e32 v144, v144
	v_rcp_f32_e32 v145, v145
	v_xor_b32_e32 v0, 16, v226
	v_add_u32_e32 v136, 64, v131
	v_cmp_lt_i32_e32 vcc, v0, v136
	v_pk_mul_f32 v[138:139], v[138:139], v[140:141]
	v_pk_mul_f32 v[142:143], v[142:143], v[144:145]
	v_cndmask_b32_e32 v0, v226, v0, vcc
	v_add_f32_e32 v140, 0, v138
	v_lshlrev_b32_e32 v131, 2, v0
	v_xor_b32_e32 v0, 32, v226
	v_add_f32_e32 v166, v139, v140
	v_cmp_lt_i32_e32 vcc, v0, v136
	v_add_f32_e32 v144, v142, v166
	v_mul_f32_e32 v140, v139, v139
	v_cndmask_b32_e32 v0, v226, v0, vcc
	v_cmp_eq_u32_e32 vcc, 0, v168
	v_add_f32_e32 v168, v143, v144
	v_pk_mul_f32 v[144:145], v[122:123], v[164:165] op_sel_hi:[1,0]
	v_pk_fma_f32 v[140:141], v[138:139], v[138:139], v[140:141] op_sel_hi:[1,1,0]
	v_mul_f32_e32 v166, 0x3d372713, v144
	v_mul_f32_e32 v167, 0x3d372713, v145
	v_mul_f32_e32 v166, v144, v166
	v_mul_f32_e32 v167, v145, v167
	v_fma_f32 v166, v144, v166, v144
	v_fma_f32 v167, v145, v167, v145
	v_mul_f32_e32 v166, 0x3fcc422a, v166
	v_mul_f32_e32 v167, 0x3fcc422a, v167
	v_mul_f32_e32 v166, 0xbfb8aa3b, v166
	v_mul_f32_e32 v167, 0xbfb8aa3b, v167
	v_exp_f32_e32 v166, v166
	v_exp_f32_e32 v167, v167
	v_pk_fma_f32 v[140:141], v[142:143], v[142:143], v[140:141]
	s_add_i32 s0, s66, -14
	v_add_f32_e32 v166, 1.0, v166
	v_add_f32_e32 v167, 1.0, v167
	v_rcp_f32_e32 v166, v166
	v_rcp_f32_e32 v167, v167
	s_lshl_b32 s1, s0, 8
	v_readlane_b32 s2, v255, 46
	s_or_b32 s1, s1, s2
	v_pk_mul_f32 v[144:145], v[144:145], v[166:167]
	v_mov_b32_e32 v167, v143
	v_add_f32_e32 v169, v144, v168
	v_mul_f32_e32 v168, v143, v143
	v_mov_b32_e32 v166, v144
	v_pk_add_f32 v[140:141], v[168:169], v[140:141] op_sel_hi:[0,1]
	v_pk_fma_f32 v[140:141], v[166:167], v[166:167], v[140:141]
	v_pk_mul_f32 v[166:167], v[124:125], v[164:165] op_sel_hi:[1,0]
	v_add_f32_e32 v170, v145, v169
	v_mul_f32_e32 v168, 0x3d372713, v166
	v_mul_f32_e32 v169, 0x3d372713, v167
	v_mul_f32_e32 v168, v166, v168
	v_mul_f32_e32 v169, v167, v169
	v_fma_f32 v168, v166, v168, v166
	v_fma_f32 v169, v167, v169, v167
	v_mul_f32_e32 v168, 0x3fcc422a, v168
	v_mul_f32_e32 v169, 0x3fcc422a, v169
	v_mul_f32_e32 v168, 0xbfb8aa3b, v168
	v_mul_f32_e32 v169, 0xbfb8aa3b, v169
	v_exp_f32_e32 v168, v168
	v_exp_f32_e32 v169, v169
	v_add_u32_e32 v134, s1, v130
	v_ashrrev_i32_e32 v135, 31, v134
	v_add_f32_e32 v168, 1.0, v168
	v_add_f32_e32 v169, 1.0, v169
	v_rcp_f32_e32 v168, v168
	v_rcp_f32_e32 v169, v169
	v_lshl_add_u64 v[134:135], v[134:135], 1, s[74:75]
	s_mov_b64 s[10:11], 0x1c4b6800
	v_lshl_add_u64 v[134:135], v[134:135], 0, s[10:11]
	v_pk_mul_f32 v[166:167], v[166:167], v[168:169]
	v_lshlrev_b64 v[136:137], 11, v[158:159]
	v_add_f32_e32 v171, v166, v170
	v_mul_f32_e32 v170, v145, v145
	v_mov_b32_e32 v168, v166
	v_mov_b32_e32 v169, v145
	v_pk_add_f32 v[140:141], v[170:171], v[140:141] op_sel_hi:[0,1]
	v_lshl_add_u64 v[136:137], v[134:135], 0, v[136:137]
	v_pk_fma_f32 v[168:169], v[168:169], v[168:169], v[140:141]
	v_cvt_pk_bf16_f32 v138, v138, v139
	v_cvt_pk_bf16_f32 v139, v142, v143
	v_cvt_pk_bf16_f32 v140, v144, v145
	v_cvt_pk_bf16_f32 v141, v166, v167
	global_store_dwordx4 v[136:137], v[138:141], off
	v_add_f32_e32 v170, v167, v171
	s_lshl_b32 s0, s0, 3
	v_pk_mul_f32 v[138:139], v[118:119], v[164:165] op_sel_hi:[1,0]
	v_readlane_b32 s1, v255, 49
	v_mul_f32_e32 v140, 0x3d372713, v138
	v_mul_f32_e32 v141, 0x3d372713, v139
	v_mul_f32_e32 v140, v138, v140
	v_mul_f32_e32 v141, v139, v141
	v_fma_f32 v140, v138, v140, v138
	v_fma_f32 v141, v139, v141, v139
	v_mul_f32_e32 v140, 0x3fcc422a, v140
	v_mul_f32_e32 v141, 0x3fcc422a, v141
	v_mul_f32_e32 v140, 0xbfb8aa3b, v140
	v_mul_f32_e32 v141, 0xbfb8aa3b, v141
	v_exp_f32_e32 v140, v140
	v_exp_f32_e32 v141, v141
	v_lshlrev_b32_e32 v0, 2, v0
	s_or_b32 s38, s0, s1
	v_add_f32_e32 v140, 1.0, v140
	v_add_f32_e32 v141, 1.0, v141
	v_rcp_f32_e32 v140, v140
	v_rcp_f32_e32 v141, v141
	s_lshl_b64 s[0:1], s[38:39], 2
	s_add_u32 s0, s74, s0
	s_addc_u32 s1, s75, s1
	v_pk_mul_f32 v[138:139], v[138:139], v[140:141]
	v_mul_f32_e32 v140, v167, v167
	v_add_f32_e32 v142, v138, v170
	v_mov_b32_e32 v166, v138
	v_pk_add_f32 v[140:141], v[140:141], v[168:169] op_sel_hi:[0,1]
	v_pk_fma_f32 v[140:141], v[166:167], v[166:167], v[140:141]
	v_add_f32_e32 v166, v139, v142
	v_pk_mul_f32 v[142:143], v[120:121], v[164:165] op_sel_hi:[1,0]
	v_cvt_pk_bf16_f32 v138, v138, v139
	v_mul_f32_e32 v144, 0x3d372713, v142
	v_mul_f32_e32 v145, 0x3d372713, v143
; __device__ __forceinline__ float sigm(float x) { return __builtin_amdgcn_rcpf(1.f + __expf(-x)); }
; __device__ __forceinline__ float gelu_tanh(float x) { return x * sigm(1.5957691216f * (x + 0.044715f * x * x * x)); }
; __device__ __forceinline__ u32x4 pack8(const float* v) { u32x4 w; w.x = cvtpk(v[0], v[1]); w.y = cvtpk(v[2], v[3]); w.z = cvtpk(v[4], v[5]); w.w = cvtpk(v[6], v[7]); return w; }
;     template <int KIND>
;     __device__ __forceinline__ void act_tile(const pg8::f32x4 (&acc)[2][2][4][2], const float (&rs)[2][4], unsigned char* w_, int row0, int colt, int statslot, int fq_) const {
;     ...
;                 for (int bj = 0; bj < 2; ++bj) {
;                     float v[8];
; #pragma unroll
;                     for (int n = 0; n < 2; ++n)
; #pragma unroll
;                         for (int j = 0; j < 4; ++j) {
;                             const float a = acc[ai][bj][m][n][j] * rs[ai][m];
;                             const float r = KIND == 2 ? sigm(a) : gelu_tanh(a);
;                             v[n * 4 + j] = r;
;                             if (KIND == 1) { s1 += r; s2 += r * r; }
;                         }
;                     *(u32x4*)(base + (size_t)row * ldc + colt + bj * 128) = pack8(v);
;                 }
;                 if (KIND == 1) {
;                     s1 += __shfl_xor(s1, 16); s1 += __shfl_xor(s1, 32); s2 += __shfl_xor(s2, 16); s2 += __shfl_xor(s2, 32);
;                     if (fq_ == 0) { float* sp = (float*)(w_ + WS_VSTAT) + ((size_t)row * 16 + statslot) * 2; sp[0] = s1; sp[1] = s2; }
;                 }
	v_mul_f32_e32 v144, v142, v144
	v_mul_f32_e32 v145, v143, v145
	v_fma_f32 v144, v142, v144, v142
	v_fma_f32 v145, v143, v145, v143
	v_mul_f32_e32 v144, 0x3fcc422a, v144
	v_mul_f32_e32 v145, 0x3fcc422a, v145
	v_mul_f32_e32 v144, 0xbfb8aa3b, v144
	v_mul_f32_e32 v145, 0xbfb8aa3b, v145
	v_exp_f32_e32 v144, v144
	v_exp_f32_e32 v145, v145
	s_add_u32 s0, s0, 0x21636800
	s_addc_u32 s1, s1, 0
	v_add_f32_e32 v144, 1.0, v144
	v_add_f32_e32 v145, 1.0, v145
	v_rcp_f32_e32 v144, v144
	v_rcp_f32_e32 v145, v145
	s_nop 0
	v_pk_mul_f32 v[142:143], v[142:143], v[144:145]
	s_nop 0
	v_add_f32_e32 v167, v142, v166
	v_mul_f32_e32 v166, v139, v139
	v_mov_b32_e32 v144, v142
	v_mov_b32_e32 v145, v139
	v_pk_add_f32 v[140:141], v[166:167], v[140:141] op_sel_hi:[0,1]
	v_pk_fma_f32 v[140:141], v[144:145], v[144:145], v[140:141]
	v_pk_mul_f32 v[144:145], v[114:115], v[164:165] op_sel_hi:[1,0]
	v_add_f32_e32 v168, v143, v167
	v_mul_f32_e32 v166, 0x3d372713, v144
	v_mul_f32_e32 v167, 0x3d372713, v145
	v_mul_f32_e32 v166, v144, v166
	v_mul_f32_e32 v167, v145, v167
	v_fma_f32 v166, v144, v166, v144
	v_fma_f32 v167, v145, v167, v145
	v_mul_f32_e32 v166, 0x3fcc422a, v166
	v_mul_f32_e32 v167, 0x3fcc422a, v167
	v_mul_f32_e32 v166, 0xbfb8aa3b, v166
	v_mul_f32_e32 v167, 0xbfb8aa3b, v167
	v_exp_f32_e32 v166, v166
	v_exp_f32_e32 v167, v167
	v_cvt_pk_bf16_f32 v139, v142, v143
	v_add_f32_e32 v166, 1.0, v166
	v_add_f32_e32 v167, 1.0, v167
	v_rcp_f32_e32 v166, v166
	v_rcp_f32_e32 v167, v167
	s_nop 0
	v_pk_mul_f32 v[144:145], v[144:145], v[166:167]
	s_nop 0
	v_add_f32_e32 v169, v144, v168
	v_mul_f32_e32 v168, v143, v143
	v_mov_b32_e32 v166, v144
	v_mov_b32_e32 v167, v143
	v_pk_add_f32 v[140:141], v[168:169], v[140:141] op_sel_hi:[0,1]
	v_pk_mul_f32 v[142:143], v[116:117], v[164:165] op_sel_hi:[1,0]
	v_pk_fma_f32 v[166:167], v[166:167], v[166:167], v[140:141]
	v_mul_f32_e32 v141, 0x3d372713, v142
	v_mul_f32_e32 v141, v142, v141
	v_fma_f32 v141, v142, v141, v142
	v_mul_f32_e32 v141, 0x3fcc422a, v141
	v_mul_f32_e32 v141, 0xbfb8aa3b, v141
	v_exp_f32_e32 v141, v141
	v_mul_f32_e32 v174, v145, v145
	v_add_f32_e32 v168, v145, v169
	v_cvt_pk_bf16_f32 v140, v144, v145
	v_add_f32_e32 v141, 1.0, v141
	v_rcp_f32_e32 v170, v141
	v_mul_f32_e32 v141, 0x3d372713, v143
	v_mul_f32_e32 v141, v143, v141
	v_fma_f32 v141, v143, v141, v143
	v_mul_f32_e32 v141, 0x3fcc422a, v141
	v_mul_f32_e32 v141, 0xbfb8aa3b, v141
	v_exp_f32_e32 v141, v141
	v_pk_add_f32 v[166:167], v[174:175], v[166:167] op_sel_hi:[0,1]
	v_add_f32_e32 v141, 1.0, v141
	v_rcp_f32_e32 v171, v141
	s_nop 0
	v_pk_mul_f32 v[172:173], v[142:143], v[170:171]
	s_nop 0
	v_mov_b32_e32 v144, v172
	v_mov_b32_e32 v169, v173
	v_pk_fma_f32 v[144:145], v[144:145], v[144:145], v[166:167]
	v_pk_fma_f32 v[142:143], v[142:143], v[170:171], v[168:169]
	v_pk_mul_f32 v[166:167], v[172:173], v[172:173]
	v_pk_mov_b32 v[144:145], v[172:173], v[144:145] op_sel:[1,0]
	v_mov_b32_e32 v143, v167
	v_pk_add_f32 v[142:143], v[142:143], v[144:145]
	v_cvt_pk_bf16_f32 v141, v172, v173
	global_store_dwordx4 v[136:137], v[138:141], off offset:256
	v_mov_b32_e32 v136, v142
	s_nop 1
	v_permlane16_swap_b32_e32 v136, v142
	v_mov_b32_e32 v137, v143
	s_nop 1
	v_permlane16_swap_b32_e32 v137, v143
	s_waitcnt lgkmcnt(0)
	v_pk_add_f32 v[136:137], v[142:143], v[136:137]
	ds_bpermute_b32 v138, v0, v136
	ds_bpermute_b32 v139, v0, v137
	s_and_saveexec_b64 s[10:11], vcc
	s_cbranch_execz .LBB0_874
	v_lshlrev_b64 v[140:141], 7, v[158:159]
	v_lshl_add_u64 v[140:141], s[0:1], 0, v[140:141]
	s_waitcnt lgkmcnt(0)
	v_pk_add_f32 v[136:137], v[136:137], v[138:139]
	global_store_dwordx2 v[140:141], v[136:137], off
.LBB0_874:
	s_or_b64 exec, exec, s[10:11]
	v_pk_mul_f32 v[140:141], v[110:111], v[164:165] op_sel:[0,1]
	v_pk_mul_f32 v[144:145], v[112:113], v[164:165] op_sel:[0,1]
	v_mul_f32_e32 v142, 0x3d372713, v140
	v_mul_f32_e32 v143, 0x3d372713, v141
	v_mul_f32_e32 v142, v140, v142
	v_mul_f32_e32 v143, v141, v143
	v_fma_f32 v142, v140, v142, v140
	v_fma_f32 v143, v141, v143, v141
	v_mul_f32_e32 v166, 0x3d372713, v144
	v_mul_f32_e32 v167, 0x3d372713, v145
	v_mul_f32_e32 v142, 0x3fcc422a, v142
	v_mul_f32_e32 v143, 0x3fcc422a, v143
	v_mul_f32_e32 v166, v144, v166
	v_mul_f32_e32 v167, v145, v167
	v_mul_f32_e32 v142, 0xbfb8aa3b, v142
	v_mul_f32_e32 v143, 0xbfb8aa3b, v143
	v_fma_f32 v166, v144, v166, v144
	v_fma_f32 v167, v145, v167, v145
	v_exp_f32_e32 v142, v142
	v_exp_f32_e32 v143, v143
	v_mul_f32_e32 v166, 0x3fcc422a, v166
	v_mul_f32_e32 v167, 0x3fcc422a, v167
	v_mul_f32_e32 v166, 0xbfb8aa3b, v166
	v_mul_f32_e32 v167, 0xbfb8aa3b, v167
	v_exp_f32_e32 v166, v166
	v_exp_f32_e32 v167, v167
	v_add_f32_e32 v142, 1.0, v142
	v_add_f32_e32 v143, 1.0, v143
	v_rcp_f32_e32 v142, v142
	v_rcp_f32_e32 v143, v143
	v_add_f32_e32 v166, 1.0, v166
	v_add_f32_e32 v167, 1.0, v167
	v_rcp_f32_e32 v166, v166
	v_rcp_f32_e32 v167, v167
	v_pk_mul_f32 v[140:141], v[140:141], v[142:143]
	v_add_u32_e32 v136, 16, v158
	v_add_f32_e32 v142, 0, v140
	v_add_f32_e32 v168, v141, v142
	v_pk_mul_f32 v[144:145], v[144:145], v[166:167]
	v_mul_f32_e32 v142, v141, v141
	v_add_f32_e32 v166, v144, v168
	v_add_f32_e32 v170, v145, v166
	v_pk_mul_f32 v[166:167], v[106:107], v[164:165] op_sel:[0,1]
	v_pk_fma_f32 v[142:143], v[140:141], v[140:141], v[142:143] op_sel_hi:[1,1,0]
	v_mul_f32_e32 v168, 0x3d372713, v166
	v_mul_f32_e32 v169, 0x3d372713, v167
	v_mul_f32_e32 v168, v166, v168
	v_mul_f32_e32 v169, v167, v169
	v_fma_f32 v168, v166, v168, v166
	v_fma_f32 v169, v167, v169, v167
	v_mul_f32_e32 v168, 0x3fcc422a, v168
	v_mul_f32_e32 v169, 0x3fcc422a, v169
	v_mul_f32_e32 v168, 0xbfb8aa3b, v168
	v_mul_f32_e32 v169, 0xbfb8aa3b, v169
	v_exp_f32_e32 v168, v168
	v_exp_f32_e32 v169, v169
	v_pk_fma_f32 v[142:143], v[144:145], v[144:145], v[142:143]
	v_ashrrev_i32_e32 v137, 31, v136
	v_add_f32_e32 v168, 1.0, v168
	v_add_f32_e32 v169, 1.0, v169
	v_rcp_f32_e32 v168, v168
	v_rcp_f32_e32 v169, v169
	s_waitcnt lgkmcnt(0)
; __device__ __forceinline__ float sigm(float x) { return __builtin_amdgcn_rcpf(1.f + __expf(-x)); }
; __device__ __forceinline__ float gelu_tanh(float x) { return x * sigm(1.5957691216f * (x + 0.044715f * x * x * x)); }
; __device__ __forceinline__ u32x4 pack8(const float* v) { u32x4 w; w.x = cvtpk(v[0], v[1]); w.y = cvtpk(v[2], v[3]); w.z = cvtpk(v[4], v[5]); w.w = cvtpk(v[6], v[7]); return w; }
;     template <int KIND>
;     __device__ __forceinline__ void act_tile(const pg8::f32x4 (&acc)[2][2][4][2], const float (&rs)[2][4], unsigned char* w_, int row0, int colt, int statslot, int fq_) const {
;     ...
;         for (int ai = 0; ai < 2; ++ai)
; #pragma unroll
;             for (int m = 0; m < 4; ++m) {
;                 const int row = row0 + ai * 128 + m * 16;
;                 float s1 = 0.f, s2 = 0.f;
; #pragma unroll
;                 for (int bj = 0; bj < 2; ++bj) {
;                     float v[8];
; #pragma unroll
;                     for (int n = 0; n < 2; ++n)
; #pragma unroll
;                         for (int j = 0; j < 4; ++j) {
;                             const float a = acc[ai][bj][m][n][j] * rs[ai][m];
;                             const float r = KIND == 2 ? sigm(a) : gelu_tanh(a);
;                             v[n * 4 + j] = r;
;                             if (KIND == 1) { s1 += r; s2 += r * r; }
;                         }
;                     *(u32x4*)(base + (size_t)row * ldc + colt + bj * 128) = pack8(v);
;                 }
;                 if (KIND == 1) {
;                     s1 += __shfl_xor(s1, 16); s1 += __shfl_xor(s1, 32); s2 += __shfl_xor(s2, 16); s2 += __shfl_xor(s2, 32);
;                     if (fq_ == 0) { float* sp = (float*)(w_ + WS_VSTAT) + ((size_t)row * 16 + statslot) * 2; sp[0] = s1; sp[1] = s2; }
;                 }
	v_lshlrev_b64 v[138:139], 11, v[136:137]
	v_lshl_add_u64 v[138:139], v[134:135], 0, v[138:139]
	v_cvt_pk_bf16_f32 v140, v140, v141
	v_pk_mul_f32 v[166:167], v[166:167], v[168:169]
	v_mov_b32_e32 v169, v145
	v_add_f32_e32 v171, v166, v170
	v_mul_f32_e32 v170, v145, v145
	v_mov_b32_e32 v168, v166
	v_pk_add_f32 v[142:143], v[170:171], v[142:143] op_sel_hi:[0,1]
	v_pk_fma_f32 v[142:143], v[168:169], v[168:169], v[142:143]
	v_pk_mul_f32 v[168:169], v[108:109], v[164:165] op_sel:[0,1]
	v_add_f32_e32 v172, v167, v171
	v_mul_f32_e32 v170, 0x3d372713, v168
	v_mul_f32_e32 v171, 0x3d372713, v169
	v_mul_f32_e32 v170, v168, v170
	v_mul_f32_e32 v171, v169, v171
	v_fma_f32 v170, v168, v170, v168
	v_fma_f32 v171, v169, v171, v169
	v_mul_f32_e32 v170, 0x3fcc422a, v170
	v_mul_f32_e32 v171, 0x3fcc422a, v171
	v_mul_f32_e32 v170, 0xbfb8aa3b, v170
	v_mul_f32_e32 v171, 0xbfb8aa3b, v171
	v_exp_f32_e32 v170, v170
	v_exp_f32_e32 v171, v171
	v_cvt_pk_bf16_f32 v141, v144, v145
	v_add_f32_e32 v170, 1.0, v170
	v_add_f32_e32 v171, 1.0, v171
	v_rcp_f32_e32 v170, v170
	v_rcp_f32_e32 v171, v171
	s_nop 0
	v_pk_mul_f32 v[168:169], v[168:169], v[170:171]
	s_nop 0
	v_add_f32_e32 v173, v168, v172
	v_mul_f32_e32 v172, v167, v167
	v_mov_b32_e32 v170, v168
	v_mov_b32_e32 v171, v167
	v_pk_add_f32 v[142:143], v[172:173], v[142:143] op_sel_hi:[0,1]
	v_pk_fma_f32 v[170:171], v[170:171], v[170:171], v[142:143]
	v_cvt_pk_bf16_f32 v142, v166, v167
	v_cvt_pk_bf16_f32 v143, v168, v169
	global_store_dwordx4 v[138:139], v[140:143], off
	v_add_f32_e32 v172, v169, v173
	s_nop 0
	v_pk_mul_f32 v[140:141], v[102:103], v[164:165] op_sel:[0,1]
	s_nop 0
	v_mul_f32_e32 v142, 0x3d372713, v140
	v_mul_f32_e32 v143, 0x3d372713, v141
	v_mul_f32_e32 v142, v140, v142
	v_mul_f32_e32 v143, v141, v143
	v_fma_f32 v142, v140, v142, v140
	v_fma_f32 v143, v141, v143, v141
	v_mul_f32_e32 v142, 0x3fcc422a, v142
	v_mul_f32_e32 v143, 0x3fcc422a, v143
	v_mul_f32_e32 v142, 0xbfb8aa3b, v142
	v_mul_f32_e32 v143, 0xbfb8aa3b, v143
	v_exp_f32_e32 v142, v142
	v_exp_f32_e32 v143, v143
	v_add_f32_e32 v142, 1.0, v142
	v_add_f32_e32 v143, 1.0, v143
	v_rcp_f32_e32 v142, v142
	v_rcp_f32_e32 v143, v143
	s_nop 0
	v_pk_mul_f32 v[140:141], v[140:141], v[142:143]
	v_mul_f32_e32 v142, v169, v169
	v_add_f32_e32 v144, v140, v172
	v_mov_b32_e32 v168, v140
	v_pk_add_f32 v[142:143], v[142:143], v[170:171] op_sel_hi:[0,1]
	v_pk_fma_f32 v[142:143], v[168:169], v[168:169], v[142:143]
	v_add_f32_e32 v168, v141, v144
	v_pk_mul_f32 v[144:145], v[104:105], v[164:165] op_sel:[0,1]
	v_cvt_pk_bf16_f32 v140, v140, v141
	v_mul_f32_e32 v166, 0x3d372713, v144
	v_mul_f32_e32 v167, 0x3d372713, v145
	v_mul_f32_e32 v166, v144, v166
	v_mul_f32_e32 v167, v145, v167
	v_fma_f32 v166, v144, v166, v144
	v_fma_f32 v167, v145, v167, v145
	v_mul_f32_e32 v166, 0x3fcc422a, v166
	v_mul_f32_e32 v167, 0x3fcc422a, v167
	v_mul_f32_e32 v166, 0xbfb8aa3b, v166
	v_mul_f32_e32 v167, 0xbfb8aa3b, v167
	v_exp_f32_e32 v166, v166
	v_exp_f32_e32 v167, v167
	v_add_f32_e32 v166, 1.0, v166
	v_add_f32_e32 v167, 1.0, v167
	v_rcp_f32_e32 v166, v166
	v_rcp_f32_e32 v167, v167
	s_nop 0
	v_pk_mul_f32 v[144:145], v[144:145], v[166:167]
	s_nop 0
	v_add_f32_e32 v169, v144, v168
	v_mul_f32_e32 v168, v141, v141
	v_mov_b32_e32 v166, v144
	v_mov_b32_e32 v167, v141
	v_pk_add_f32 v[142:143], v[168:169], v[142:143] op_sel_hi:[0,1]
	v_pk_fma_f32 v[142:143], v[166:167], v[166:167], v[142:143]
	v_pk_mul_f32 v[166:167], v[98:99], v[164:165] op_sel:[0,1]
	v_add_f32_e32 v170, v145, v169
	v_mul_f32_e32 v168, 0x3d372713, v166
	v_mul_f32_e32 v169, 0x3d372713, v167
	v_mul_f32_e32 v168, v166, v168
	v_mul_f32_e32 v169, v167, v169
	v_fma_f32 v168, v166, v168, v166
	v_fma_f32 v169, v167, v169, v167
	v_mul_f32_e32 v168, 0x3fcc422a, v168
	v_mul_f32_e32 v169, 0x3fcc422a, v169
	v_mul_f32_e32 v168, 0xbfb8aa3b, v168
	v_mul_f32_e32 v169, 0xbfb8aa3b, v169
	v_exp_f32_e32 v168, v168
	v_exp_f32_e32 v169, v169
	v_cvt_pk_bf16_f32 v141, v144, v145
	v_add_f32_e32 v168, 1.0, v168
	v_add_f32_e32 v169, 1.0, v169
	v_rcp_f32_e32 v168, v168
	v_rcp_f32_e32 v169, v169
	s_nop 0
	v_pk_mul_f32 v[166:167], v[166:167], v[168:169]
	s_nop 0
	v_add_f32_e32 v171, v166, v170
	v_mul_f32_e32 v170, v145, v145
	v_mov_b32_e32 v168, v166
	v_mov_b32_e32 v169, v145
	v_pk_add_f32 v[142:143], v[170:171], v[142:143] op_sel_hi:[0,1]
	v_pk_mul_f32 v[144:145], v[100:101], v[164:165] op_sel:[0,1]
	v_pk_fma_f32 v[168:169], v[168:169], v[168:169], v[142:143]
	v_mul_f32_e32 v143, 0x3d372713, v144
	v_mul_f32_e32 v143, v144, v143
	v_fma_f32 v143, v144, v143, v144
	v_mul_f32_e32 v143, 0x3fcc422a, v143
	v_mul_f32_e32 v143, 0xbfb8aa3b, v143
	v_exp_f32_e32 v143, v143
	v_mul_f32_e32 v176, v167, v167
	v_add_f32_e32 v170, v167, v171
	v_cvt_pk_bf16_f32 v142, v166, v167
	v_add_f32_e32 v143, 1.0, v143
	v_rcp_f32_e32 v172, v143
	v_mul_f32_e32 v143, 0x3d372713, v145
	v_mul_f32_e32 v143, v145, v143
	v_fma_f32 v143, v145, v143, v145
	v_mul_f32_e32 v143, 0x3fcc422a, v143
	v_mul_f32_e32 v143, 0xbfb8aa3b, v143
	v_exp_f32_e32 v143, v143
	v_pk_add_f32 v[168:169], v[176:177], v[168:169] op_sel_hi:[0,1]
	v_add_f32_e32 v143, 1.0, v143
	v_rcp_f32_e32 v173, v143
	s_nop 0
	v_pk_mul_f32 v[174:175], v[144:145], v[172:173]
	s_nop 0
	v_mov_b32_e32 v166, v174
	v_mov_b32_e32 v171, v175
	v_pk_fma_f32 v[166:167], v[166:167], v[166:167], v[168:169]
	v_pk_fma_f32 v[144:145], v[144:145], v[172:173], v[170:171]
	v_pk_mul_f32 v[168:169], v[174:175], v[174:175]
	v_pk_mov_b32 v[166:167], v[174:175], v[166:167] op_sel:[1,0]
	v_mov_b32_e32 v145, v169
	v_pk_add_f32 v[144:145], v[144:145], v[166:167]
	v_cvt_pk_bf16_f32 v143, v174, v175
	global_store_dwordx4 v[138:139], v[140:143], off offset:256
	v_mov_b32_e32 v138, v144
	s_nop 1
	v_permlane16_swap_b32_e32 v138, v144
	v_mov_b32_e32 v139, v145
	s_nop 1
	v_permlane16_swap_b32_e32 v139, v145
	s_waitcnt lgkmcnt(0)
	v_pk_add_f32 v[138:139], v[144:145], v[138:139]
	ds_bpermute_b32 v140, v0, v138
	ds_bpermute_b32 v141, v0, v139
	s_and_saveexec_b64 s[10:11], vcc
	s_cbranch_execz .LBB0_876
	v_lshlrev_b64 v[136:137], 7, v[136:137]
	v_lshl_add_u64 v[136:137], s[0:1], 0, v[136:137]
	s_waitcnt lgkmcnt(0)
	v_pk_add_f32 v[138:139], v[138:139], v[140:141]
	global_store_dwordx2 v[136:137], v[138:139], off
; __device__ __forceinline__ float sigm(float x) { return __builtin_amdgcn_rcpf(1.f + __expf(-x)); }
; __device__ __forceinline__ float gelu_tanh(float x) { return x * sigm(1.5957691216f * (x + 0.044715f * x * x * x)); }
; __device__ __forceinline__ u32x4 pack8(const float* v) { u32x4 w; w.x = cvtpk(v[0], v[1]); w.y = cvtpk(v[2], v[3]); w.z = cvtpk(v[4], v[5]); w.w = cvtpk(v[6], v[7]); return w; }
;     template <int KIND>
;     __device__ __forceinline__ void act_tile(const pg8::f32x4 (&acc)[2][2][4][2], const float (&rs)[2][4], unsigned char* w_, int row0, int colt, int statslot, int fq_) const {
;     ...
;         for (int ai = 0; ai < 2; ++ai)
; #pragma unroll
;             for (int m = 0; m < 4; ++m) {
;                 const int row = row0 + ai * 128 + m * 16;
;                 float s1 = 0.f, s2 = 0.f;
; #pragma unroll
;                 for (int bj = 0; bj < 2; ++bj) {
;                     float v[8];
; #pragma unroll
;                     for (int n = 0; n < 2; ++n)
; #pragma unroll
;                         for (int j = 0; j < 4; ++j) {
;                             const float a = acc[ai][bj][m][n][j] * rs[ai][m];
;                             const float r = KIND == 2 ? sigm(a) : gelu_tanh(a);
;                             v[n * 4 + j] = r;
;                             if (KIND == 1) { s1 += r; s2 += r * r; }
;                         }
;                     *(u32x4*)(base + (size_t)row * ldc + colt + bj * 128) = pack8(v);
;                 }
;                 if (KIND == 1) {
;                     s1 += __shfl_xor(s1, 16); s1 += __shfl_xor(s1, 32); s2 += __shfl_xor(s2, 16); s2 += __shfl_xor(s2, 32);
.LBB0_876:
	s_or_b64 exec, exec, s[10:11]
	s_waitcnt lgkmcnt(0)
	v_pk_mul_f32 v[140:141], v[94:95], v[162:163] op_sel_hi:[1,0]
	v_pk_mul_f32 v[144:145], v[96:97], v[162:163] op_sel_hi:[1,0]
	v_mul_f32_e32 v142, 0x3d372713, v140
	v_mul_f32_e32 v143, 0x3d372713, v141
	v_mul_f32_e32 v142, v140, v142
	v_mul_f32_e32 v143, v141, v143
	v_fma_f32 v142, v140, v142, v140
	v_fma_f32 v143, v141, v143, v141
	v_mul_f32_e32 v166, 0x3d372713, v144
	v_mul_f32_e32 v167, 0x3d372713, v145
	v_mul_f32_e32 v142, 0x3fcc422a, v142
	v_mul_f32_e32 v143, 0x3fcc422a, v143
	v_mul_f32_e32 v166, v144, v166
	v_mul_f32_e32 v167, v145, v167
	v_mul_f32_e32 v142, 0xbfb8aa3b, v142
	v_mul_f32_e32 v143, 0xbfb8aa3b, v143
	v_fma_f32 v166, v144, v166, v144
	v_fma_f32 v167, v145, v167, v145
	v_exp_f32_e32 v142, v142
	v_exp_f32_e32 v143, v143
	v_mul_f32_e32 v166, 0x3fcc422a, v166
	v_mul_f32_e32 v167, 0x3fcc422a, v167
	v_mul_f32_e32 v166, 0xbfb8aa3b, v166
	v_mul_f32_e32 v167, 0xbfb8aa3b, v167
	v_exp_f32_e32 v166, v166
	v_exp_f32_e32 v167, v167
	v_add_f32_e32 v142, 1.0, v142
	v_add_f32_e32 v143, 1.0, v143
	v_rcp_f32_e32 v142, v142
	v_rcp_f32_e32 v143, v143
	v_add_f32_e32 v166, 1.0, v166
	v_add_f32_e32 v167, 1.0, v167
	v_rcp_f32_e32 v166, v166
	v_rcp_f32_e32 v167, v167
	v_pk_mul_f32 v[140:141], v[140:141], v[142:143]
	v_add_u32_e32 v136, 32, v158
	v_add_f32_e32 v142, 0, v140
	v_add_f32_e32 v168, v141, v142
	v_pk_mul_f32 v[144:145], v[144:145], v[166:167]
	v_mul_f32_e32 v142, v141, v141
	v_add_f32_e32 v166, v144, v168
	v_add_f32_e32 v170, v145, v166
	v_pk_mul_f32 v[166:167], v[90:91], v[162:163] op_sel_hi:[1,0]
	v_pk_fma_f32 v[142:143], v[140:141], v[140:141], v[142:143] op_sel_hi:[1,1,0]
	v_mul_f32_e32 v168, 0x3d372713, v166
	v_mul_f32_e32 v169, 0x3d372713, v167
	v_mul_f32_e32 v168, v166, v168
	v_mul_f32_e32 v169, v167, v169
	v_fma_f32 v168, v166, v168, v166
	v_fma_f32 v169, v167, v169, v167
	v_mul_f32_e32 v168, 0x3fcc422a, v168
	v_mul_f32_e32 v169, 0x3fcc422a, v169
	v_mul_f32_e32 v168, 0xbfb8aa3b, v168
	v_mul_f32_e32 v169, 0xbfb8aa3b, v169
	v_exp_f32_e32 v168, v168
	v_exp_f32_e32 v169, v169
	v_pk_fma_f32 v[142:143], v[144:145], v[144:145], v[142:143]
	v_ashrrev_i32_e32 v137, 31, v136
	v_add_f32_e32 v168, 1.0, v168
	v_add_f32_e32 v169, 1.0, v169
	v_rcp_f32_e32 v168, v168
	v_rcp_f32_e32 v169, v169
	v_lshlrev_b64 v[138:139], 11, v[136:137]
	v_lshl_add_u64 v[138:139], v[134:135], 0, v[138:139]
	v_cvt_pk_bf16_f32 v140, v140, v141
	v_pk_mul_f32 v[166:167], v[166:167], v[168:169]
	v_mov_b32_e32 v169, v145
	v_add_f32_e32 v171, v166, v170
	v_mul_f32_e32 v170, v145, v145
	v_mov_b32_e32 v168, v166
	v_pk_add_f32 v[142:143], v[170:171], v[142:143] op_sel_hi:[0,1]
	v_pk_fma_f32 v[142:143], v[168:169], v[168:169], v[142:143]
	v_pk_mul_f32 v[168:169], v[92:93], v[162:163] op_sel_hi:[1,0]
	v_add_f32_e32 v172, v167, v171
	v_mul_f32_e32 v170, 0x3d372713, v168
	v_mul_f32_e32 v171, 0x3d372713, v169
	v_mul_f32_e32 v170, v168, v170
	v_mul_f32_e32 v171, v169, v171
	v_fma_f32 v170, v168, v170, v168
	v_fma_f32 v171, v169, v171, v169
	v_mul_f32_e32 v170, 0x3fcc422a, v170
	v_mul_f32_e32 v171, 0x3fcc422a, v171
	v_mul_f32_e32 v170, 0xbfb8aa3b, v170
	v_mul_f32_e32 v171, 0xbfb8aa3b, v171
	v_exp_f32_e32 v170, v170
	v_exp_f32_e32 v171, v171
	v_cvt_pk_bf16_f32 v141, v144, v145
	v_add_f32_e32 v170, 1.0, v170
	v_add_f32_e32 v171, 1.0, v171
	v_rcp_f32_e32 v170, v170
	v_rcp_f32_e32 v171, v171
	s_nop 0
	v_pk_mul_f32 v[168:169], v[168:169], v[170:171]
	s_nop 0
	v_add_f32_e32 v173, v168, v172
	v_mul_f32_e32 v172, v167, v167
	v_mov_b32_e32 v170, v168
	v_mov_b32_e32 v171, v167
	v_pk_add_f32 v[142:143], v[172:173], v[142:143] op_sel_hi:[0,1]
	v_pk_fma_f32 v[170:171], v[170:171], v[170:171], v[142:143]
	v_cvt_pk_bf16_f32 v142, v166, v167
	v_cvt_pk_bf16_f32 v143, v168, v169
	global_store_dwordx4 v[138:139], v[140:143], off
	v_add_f32_e32 v172, v169, v173
	s_nop 0
	v_pk_mul_f32 v[140:141], v[86:87], v[162:163] op_sel_hi:[1,0]
	s_nop 0
	v_mul_f32_e32 v142, 0x3d372713, v140
	v_mul_f32_e32 v143, 0x3d372713, v141
	v_mul_f32_e32 v142, v140, v142
	v_mul_f32_e32 v143, v141, v143
	v_fma_f32 v142, v140, v142, v140
	v_fma_f32 v143, v141, v143, v141
	v_mul_f32_e32 v142, 0x3fcc422a, v142
	v_mul_f32_e32 v143, 0x3fcc422a, v143
	v_mul_f32_e32 v142, 0xbfb8aa3b, v142
	v_mul_f32_e32 v143, 0xbfb8aa3b, v143
	v_exp_f32_e32 v142, v142
	v_exp_f32_e32 v143, v143
	v_add_f32_e32 v142, 1.0, v142
	v_add_f32_e32 v143, 1.0, v143
	v_rcp_f32_e32 v142, v142
	v_rcp_f32_e32 v143, v143
	s_nop 0
	v_pk_mul_f32 v[140:141], v[140:141], v[142:143]
	v_mul_f32_e32 v142, v169, v169
	v_add_f32_e32 v144, v140, v172
	v_mov_b32_e32 v168, v140
	v_pk_add_f32 v[142:143], v[142:143], v[170:171] op_sel_hi:[0,1]
	v_pk_fma_f32 v[142:143], v[168:169], v[168:169], v[142:143]
	v_add_f32_e32 v168, v141, v144
	v_pk_mul_f32 v[144:145], v[88:89], v[162:163] op_sel_hi:[1,0]
	v_cvt_pk_bf16_f32 v140, v140, v141
	v_mul_f32_e32 v166, 0x3d372713, v144
	v_mul_f32_e32 v167, 0x3d372713, v145
	v_mul_f32_e32 v166, v144, v166
	v_mul_f32_e32 v167, v145, v167
	v_fma_f32 v166, v144, v166, v144
	v_fma_f32 v167, v145, v167, v145
	v_mul_f32_e32 v166, 0x3fcc422a, v166
	v_mul_f32_e32 v167, 0x3fcc422a, v167
	v_mul_f32_e32 v166, 0xbfb8aa3b, v166
	v_mul_f32_e32 v167, 0xbfb8aa3b, v167
	v_exp_f32_e32 v166, v166
	v_exp_f32_e32 v167, v167
	v_add_f32_e32 v166, 1.0, v166
	v_add_f32_e32 v167, 1.0, v167
	v_rcp_f32_e32 v166, v166
	v_rcp_f32_e32 v167, v167
	s_nop 0
	v_pk_mul_f32 v[144:145], v[144:145], v[166:167]
	s_nop 0
	v_add_f32_e32 v169, v144, v168
	v_mul_f32_e32 v168, v141, v141
	v_mov_b32_e32 v166, v144
	v_mov_b32_e32 v167, v141
	v_pk_add_f32 v[142:143], v[168:169], v[142:143] op_sel_hi:[0,1]
; __device__ __forceinline__ float sigm(float x) { return __builtin_amdgcn_rcpf(1.f + __expf(-x)); }
; __device__ __forceinline__ float gelu_tanh(float x) { return x * sigm(1.5957691216f * (x + 0.044715f * x * x * x)); }
; __device__ __forceinline__ u32x4 pack8(const float* v) { u32x4 w; w.x = cvtpk(v[0], v[1]); w.y = cvtpk(v[2], v[3]); w.z = cvtpk(v[4], v[5]); w.w = cvtpk(v[6], v[7]); return w; }
;     template <int KIND>
;     __device__ __forceinline__ void act_tile(const pg8::f32x4 (&acc)[2][2][4][2], const float (&rs)[2][4], unsigned char* w_, int row0, int colt, int statslot, int fq_) const {
;     ...
;         for (int ai = 0; ai < 2; ++ai)
; #pragma unroll
;             for (int m = 0; m < 4; ++m) {
;                 const int row = row0 + ai * 128 + m * 16;
;                 float s1 = 0.f, s2 = 0.f;
; #pragma unroll
;                 for (int bj = 0; bj < 2; ++bj) {
;                     float v[8];
; #pragma unroll
;                     for (int n = 0; n < 2; ++n)
; #pragma unroll
;                         for (int j = 0; j < 4; ++j) {
;                             const float a = acc[ai][bj][m][n][j] * rs[ai][m];
;                             const float r = KIND == 2 ? sigm(a) : gelu_tanh(a);
;                             v[n * 4 + j] = r;
;                             if (KIND == 1) { s1 += r; s2 += r * r; }
;                         }
;                     *(u32x4*)(base + (size_t)row * ldc + colt + bj * 128) = pack8(v);
;                 }
;                 if (KIND == 1) {
;                     s1 += __shfl_xor(s1, 16); s1 += __shfl_xor(s1, 32); s2 += __shfl_xor(s2, 16); s2 += __shfl_xor(s2, 32);
;                     if (fq_ == 0) { float* sp = (float*)(w_ + WS_VSTAT) + ((size_t)row * 16 + statslot) * 2; sp[0] = s1; sp[1] = s2; }
;                 }
	v_pk_fma_f32 v[142:143], v[166:167], v[166:167], v[142:143]
	v_pk_mul_f32 v[166:167], v[82:83], v[162:163] op_sel_hi:[1,0]
	v_add_f32_e32 v170, v145, v169
	v_mul_f32_e32 v168, 0x3d372713, v166
	v_mul_f32_e32 v169, 0x3d372713, v167
	v_mul_f32_e32 v168, v166, v168
	v_mul_f32_e32 v169, v167, v169
	v_fma_f32 v168, v166, v168, v166
	v_fma_f32 v169, v167, v169, v167
	v_mul_f32_e32 v168, 0x3fcc422a, v168
	v_mul_f32_e32 v169, 0x3fcc422a, v169
	v_mul_f32_e32 v168, 0xbfb8aa3b, v168
	v_mul_f32_e32 v169, 0xbfb8aa3b, v169
	v_exp_f32_e32 v168, v168
	v_exp_f32_e32 v169, v169
	v_cvt_pk_bf16_f32 v141, v144, v145
	v_add_f32_e32 v168, 1.0, v168
	v_add_f32_e32 v169, 1.0, v169
	v_rcp_f32_e32 v168, v168
	v_rcp_f32_e32 v169, v169
	s_nop 0
	v_pk_mul_f32 v[166:167], v[166:167], v[168:169]
	s_nop 0
	v_add_f32_e32 v171, v166, v170
	v_mul_f32_e32 v170, v145, v145
	v_mov_b32_e32 v168, v166
	v_mov_b32_e32 v169, v145
	v_pk_add_f32 v[142:143], v[170:171], v[142:143] op_sel_hi:[0,1]
	v_pk_mul_f32 v[144:145], v[84:85], v[162:163] op_sel_hi:[1,0]
	v_pk_fma_f32 v[168:169], v[168:169], v[168:169], v[142:143]
	v_mul_f32_e32 v143, 0x3d372713, v144
	v_mul_f32_e32 v143, v144, v143
	v_fma_f32 v143, v144, v143, v144
	v_mul_f32_e32 v143, 0x3fcc422a, v143
	v_mul_f32_e32 v143, 0xbfb8aa3b, v143
	v_exp_f32_e32 v143, v143
	v_mul_f32_e32 v176, v167, v167
	v_add_f32_e32 v170, v167, v171
	v_cvt_pk_bf16_f32 v142, v166, v167
	v_add_f32_e32 v143, 1.0, v143
	v_rcp_f32_e32 v172, v143
	v_mul_f32_e32 v143, 0x3d372713, v145
	v_mul_f32_e32 v143, v145, v143
	v_fma_f32 v143, v145, v143, v145
	v_mul_f32_e32 v143, 0x3fcc422a, v143
	v_mul_f32_e32 v143, 0xbfb8aa3b, v143
	v_exp_f32_e32 v143, v143
	v_pk_add_f32 v[168:169], v[176:177], v[168:169] op_sel_hi:[0,1]
	v_add_f32_e32 v143, 1.0, v143
	v_rcp_f32_e32 v173, v143
	s_nop 0
	v_pk_mul_f32 v[174:175], v[144:145], v[172:173]
	s_nop 0
	v_mov_b32_e32 v166, v174
	v_mov_b32_e32 v171, v175
	v_pk_fma_f32 v[166:167], v[166:167], v[166:167], v[168:169]
	v_pk_fma_f32 v[144:145], v[144:145], v[172:173], v[170:171]
	v_pk_mul_f32 v[168:169], v[174:175], v[174:175]
	v_pk_mov_b32 v[166:167], v[174:175], v[166:167] op_sel:[1,0]
	v_mov_b32_e32 v145, v169
	v_pk_add_f32 v[144:145], v[144:145], v[166:167]
	v_cvt_pk_bf16_f32 v143, v174, v175
	global_store_dwordx4 v[138:139], v[140:143], off offset:256
	v_mov_b32_e32 v138, v144
	s_nop 1
	v_permlane16_swap_b32_e32 v138, v144
	v_mov_b32_e32 v139, v145
	s_nop 1
	v_permlane16_swap_b32_e32 v139, v145
	s_waitcnt lgkmcnt(0)
	v_pk_add_f32 v[138:139], v[144:145], v[138:139]
	ds_bpermute_b32 v140, v0, v138
	ds_bpermute_b32 v141, v0, v139
	s_and_saveexec_b64 s[10:11], vcc
	s_movk_i32 s38, 0x6000
	s_cbranch_execz .LBB0_878
	v_lshlrev_b64 v[136:137], 7, v[136:137]
	v_lshl_add_u64 v[136:137], s[0:1], 0, v[136:137]
	s_waitcnt lgkmcnt(0)
	v_pk_add_f32 v[138:139], v[138:139], v[140:141]
	global_store_dwordx2 v[136:137], v[138:139], off
.LBB0_878:
	s_or_b64 exec, exec, s[10:11]
	s_waitcnt lgkmcnt(0)
	v_pk_mul_f32 v[140:141], v[78:79], v[162:163] op_sel:[0,1]
	v_pk_mul_f32 v[144:145], v[80:81], v[162:163] op_sel:[0,1]
	v_mul_f32_e32 v142, 0x3d372713, v140
	v_mul_f32_e32 v143, 0x3d372713, v141
	v_mul_f32_e32 v142, v140, v142
	v_mul_f32_e32 v143, v141, v143
	v_fma_f32 v142, v140, v142, v140
	v_fma_f32 v143, v141, v143, v141
	v_mul_f32_e32 v166, 0x3d372713, v144
	v_mul_f32_e32 v167, 0x3d372713, v145
	v_mul_f32_e32 v142, 0x3fcc422a, v142
	v_mul_f32_e32 v143, 0x3fcc422a, v143
	v_mul_f32_e32 v166, v144, v166
	v_mul_f32_e32 v167, v145, v167
	v_mul_f32_e32 v142, 0xbfb8aa3b, v142
	v_mul_f32_e32 v143, 0xbfb8aa3b, v143
	v_fma_f32 v166, v144, v166, v144
	v_fma_f32 v167, v145, v167, v145
	v_exp_f32_e32 v142, v142
	v_exp_f32_e32 v143, v143
	v_mul_f32_e32 v166, 0x3fcc422a, v166
	v_mul_f32_e32 v167, 0x3fcc422a, v167
	v_mul_f32_e32 v166, 0xbfb8aa3b, v166
	v_mul_f32_e32 v167, 0xbfb8aa3b, v167
	v_exp_f32_e32 v166, v166
	v_exp_f32_e32 v167, v167
	v_add_f32_e32 v142, 1.0, v142
	v_add_f32_e32 v143, 1.0, v143
	v_rcp_f32_e32 v142, v142
	v_rcp_f32_e32 v143, v143
	v_add_f32_e32 v166, 1.0, v166
	v_add_f32_e32 v167, 1.0, v167
	v_rcp_f32_e32 v166, v166
	v_rcp_f32_e32 v167, v167
	v_pk_mul_f32 v[140:141], v[140:141], v[142:143]
	v_add_u32_e32 v136, 48, v158
	v_add_f32_e32 v142, 0, v140
	v_add_f32_e32 v168, v141, v142
	v_pk_mul_f32 v[144:145], v[144:145], v[166:167]
	v_mul_f32_e32 v142, v141, v141
	v_add_f32_e32 v166, v144, v168
	v_add_f32_e32 v170, v145, v166
	v_pk_mul_f32 v[166:167], v[74:75], v[162:163] op_sel:[0,1]
	v_pk_fma_f32 v[142:143], v[140:141], v[140:141], v[142:143] op_sel_hi:[1,1,0]
	v_mul_f32_e32 v168, 0x3d372713, v166
	v_mul_f32_e32 v169, 0x3d372713, v167
	v_mul_f32_e32 v168, v166, v168
	v_mul_f32_e32 v169, v167, v169
	v_fma_f32 v168, v166, v168, v166
	v_fma_f32 v169, v167, v169, v167
	v_mul_f32_e32 v168, 0x3fcc422a, v168
	v_mul_f32_e32 v169, 0x3fcc422a, v169
	v_mul_f32_e32 v168, 0xbfb8aa3b, v168
	v_mul_f32_e32 v169, 0xbfb8aa3b, v169
	v_exp_f32_e32 v168, v168
	v_exp_f32_e32 v169, v169
	v_pk_fma_f32 v[142:143], v[144:145], v[144:145], v[142:143]
	v_ashrrev_i32_e32 v137, 31, v136
	v_add_f32_e32 v168, 1.0, v168
	v_add_f32_e32 v169, 1.0, v169
	v_rcp_f32_e32 v168, v168
	v_rcp_f32_e32 v169, v169
	v_lshlrev_b64 v[138:139], 11, v[136:137]
	v_lshl_add_u64 v[138:139], v[134:135], 0, v[138:139]
	v_cvt_pk_bf16_f32 v140, v140, v141
	v_pk_mul_f32 v[166:167], v[166:167], v[168:169]
	v_mov_b32_e32 v169, v145
	v_add_f32_e32 v171, v166, v170
	v_mul_f32_e32 v170, v145, v145
	v_mov_b32_e32 v168, v166
	v_pk_add_f32 v[142:143], v[170:171], v[142:143] op_sel_hi:[0,1]
	v_pk_fma_f32 v[142:143], v[168:169], v[168:169], v[142:143]
	v_pk_mul_f32 v[168:169], v[76:77], v[162:163] op_sel:[0,1]
; __device__ __forceinline__ float sigm(float x) { return __builtin_amdgcn_rcpf(1.f + __expf(-x)); }
; __device__ __forceinline__ float gelu_tanh(float x) { return x * sigm(1.5957691216f * (x + 0.044715f * x * x * x)); }
; __device__ __forceinline__ u32x4 pack8(const float* v) { u32x4 w; w.x = cvtpk(v[0], v[1]); w.y = cvtpk(v[2], v[3]); w.z = cvtpk(v[4], v[5]); w.w = cvtpk(v[6], v[7]); return w; }
;     template <int KIND>
;     __device__ __forceinline__ void act_tile(const pg8::f32x4 (&acc)[2][2][4][2], const float (&rs)[2][4], unsigned char* w_, int row0, int colt, int statslot, int fq_) const {
;     ...
;         for (int ai = 0; ai < 2; ++ai)
; #pragma unroll
;             for (int m = 0; m < 4; ++m) {
;                 const int row = row0 + ai * 128 + m * 16;
;                 float s1 = 0.f, s2 = 0.f;
; #pragma unroll
;                 for (int bj = 0; bj < 2; ++bj) {
;                     float v[8];
; #pragma unroll
;                     for (int n = 0; n < 2; ++n)
; #pragma unroll
;                         for (int j = 0; j < 4; ++j) {
;                             const float a = acc[ai][bj][m][n][j] * rs[ai][m];
;                             const float r = KIND == 2 ? sigm(a) : gelu_tanh(a);
;                             v[n * 4 + j] = r;
;                             if (KIND == 1) { s1 += r; s2 += r * r; }
;                         }
;                     *(u32x4*)(base + (size_t)row * ldc + colt + bj * 128) = pack8(v);
;                 }
;                 if (KIND == 1) {
;                     s1 += __shfl_xor(s1, 16); s1 += __shfl_xor(s1, 32); s2 += __shfl_xor(s2, 16); s2 += __shfl_xor(s2, 32);
;                     if (fq_ == 0) { float* sp = (float*)(w_ + WS_VSTAT) + ((size_t)row * 16 + statslot) * 2; sp[0] = s1; sp[1] = s2; }
;                 }
	v_add_f32_e32 v172, v167, v171
	v_mul_f32_e32 v170, 0x3d372713, v168
	v_mul_f32_e32 v171, 0x3d372713, v169
	v_mul_f32_e32 v170, v168, v170
	v_mul_f32_e32 v171, v169, v171
	v_fma_f32 v170, v168, v170, v168
	v_fma_f32 v171, v169, v171, v169
	v_mul_f32_e32 v170, 0x3fcc422a, v170
	v_mul_f32_e32 v171, 0x3fcc422a, v171
	v_mul_f32_e32 v170, 0xbfb8aa3b, v170
	v_mul_f32_e32 v171, 0xbfb8aa3b, v171
	v_exp_f32_e32 v170, v170
	v_exp_f32_e32 v171, v171
	v_cvt_pk_bf16_f32 v141, v144, v145
	v_add_f32_e32 v170, 1.0, v170
	v_add_f32_e32 v171, 1.0, v171
	v_rcp_f32_e32 v170, v170
	v_rcp_f32_e32 v171, v171
	s_nop 0
	v_pk_mul_f32 v[168:169], v[168:169], v[170:171]
	s_nop 0
	v_add_f32_e32 v173, v168, v172
	v_mul_f32_e32 v172, v167, v167
	v_mov_b32_e32 v170, v168
	v_mov_b32_e32 v171, v167
	v_pk_add_f32 v[142:143], v[172:173], v[142:143] op_sel_hi:[0,1]
	v_pk_fma_f32 v[170:171], v[170:171], v[170:171], v[142:143]
	v_cvt_pk_bf16_f32 v142, v166, v167
	v_cvt_pk_bf16_f32 v143, v168, v169
	global_store_dwordx4 v[138:139], v[140:143], off
	v_add_f32_e32 v172, v169, v173
	s_nop 0
	v_pk_mul_f32 v[140:141], v[70:71], v[162:163] op_sel:[0,1]
	s_nop 0
	v_mul_f32_e32 v142, 0x3d372713, v140
	v_mul_f32_e32 v143, 0x3d372713, v141
	v_mul_f32_e32 v142, v140, v142
	v_mul_f32_e32 v143, v141, v143
	v_fma_f32 v142, v140, v142, v140
	v_fma_f32 v143, v141, v143, v141
	v_mul_f32_e32 v142, 0x3fcc422a, v142
	v_mul_f32_e32 v143, 0x3fcc422a, v143
	v_mul_f32_e32 v142, 0xbfb8aa3b, v142
	v_mul_f32_e32 v143, 0xbfb8aa3b, v143
	v_exp_f32_e32 v142, v142
	v_exp_f32_e32 v143, v143
	v_add_f32_e32 v142, 1.0, v142
	v_add_f32_e32 v143, 1.0, v143
	v_rcp_f32_e32 v142, v142
	v_rcp_f32_e32 v143, v143
	s_nop 0
	v_pk_mul_f32 v[140:141], v[140:141], v[142:143]
	v_mul_f32_e32 v142, v169, v169
	v_add_f32_e32 v144, v140, v172
	v_mov_b32_e32 v168, v140
	v_pk_add_f32 v[142:143], v[142:143], v[170:171] op_sel_hi:[0,1]
	v_pk_fma_f32 v[142:143], v[168:169], v[168:169], v[142:143]
	v_add_f32_e32 v168, v141, v144
	v_pk_mul_f32 v[144:145], v[72:73], v[162:163] op_sel:[0,1]
	v_cvt_pk_bf16_f32 v140, v140, v141
	v_mul_f32_e32 v166, 0x3d372713, v144
	v_mul_f32_e32 v167, 0x3d372713, v145
	v_mul_f32_e32 v166, v144, v166
	v_mul_f32_e32 v167, v145, v167
	v_fma_f32 v166, v144, v166, v144
	v_fma_f32 v167, v145, v167, v145
	v_mul_f32_e32 v166, 0x3fcc422a, v166
	v_mul_f32_e32 v167, 0x3fcc422a, v167
	v_mul_f32_e32 v166, 0xbfb8aa3b, v166
	v_mul_f32_e32 v167, 0xbfb8aa3b, v167
	v_exp_f32_e32 v166, v166
	v_exp_f32_e32 v167, v167
	v_add_f32_e32 v166, 1.0, v166
	v_add_f32_e32 v167, 1.0, v167
	v_rcp_f32_e32 v166, v166
	v_rcp_f32_e32 v167, v167
	s_nop 0
	v_pk_mul_f32 v[144:145], v[144:145], v[166:167]
	s_nop 0
	v_add_f32_e32 v169, v144, v168
	v_mul_f32_e32 v168, v141, v141
	v_mov_b32_e32 v166, v144
	v_mov_b32_e32 v167, v141
	v_pk_add_f32 v[142:143], v[168:169], v[142:143] op_sel_hi:[0,1]
	v_pk_fma_f32 v[142:143], v[166:167], v[166:167], v[142:143]
	v_pk_mul_f32 v[166:167], v[66:67], v[162:163] op_sel:[0,1]
	v_add_f32_e32 v170, v145, v169
	v_mul_f32_e32 v168, 0x3d372713, v166
	v_mul_f32_e32 v169, 0x3d372713, v167
	v_mul_f32_e32 v168, v166, v168
	v_mul_f32_e32 v169, v167, v169
	v_fma_f32 v168, v166, v168, v166
	v_fma_f32 v169, v167, v169, v167
	v_mul_f32_e32 v168, 0x3fcc422a, v168
	v_mul_f32_e32 v169, 0x3fcc422a, v169
	v_mul_f32_e32 v168, 0xbfb8aa3b, v168
	v_mul_f32_e32 v169, 0xbfb8aa3b, v169
	v_exp_f32_e32 v168, v168
	v_exp_f32_e32 v169, v169
	v_cvt_pk_bf16_f32 v141, v144, v145
	v_add_f32_e32 v168, 1.0, v168
	v_add_f32_e32 v169, 1.0, v169
	v_rcp_f32_e32 v168, v168
	v_rcp_f32_e32 v169, v169
	s_nop 0
	v_pk_mul_f32 v[166:167], v[166:167], v[168:169]
	s_nop 0
	v_add_f32_e32 v171, v166, v170
	v_mul_f32_e32 v170, v145, v145
	v_mov_b32_e32 v168, v166
	v_mov_b32_e32 v169, v145
	v_pk_add_f32 v[142:143], v[170:171], v[142:143] op_sel_hi:[0,1]
	v_pk_mul_f32 v[144:145], v[68:69], v[162:163] op_sel:[0,1]
	v_pk_fma_f32 v[168:169], v[168:169], v[168:169], v[142:143]
	v_mul_f32_e32 v143, 0x3d372713, v144
	v_mul_f32_e32 v143, v144, v143
	v_fma_f32 v143, v144, v143, v144
	v_mul_f32_e32 v143, 0x3fcc422a, v143
	v_mul_f32_e32 v143, 0xbfb8aa3b, v143
	v_exp_f32_e32 v143, v143
	v_mul_f32_e32 v176, v167, v167
	v_add_f32_e32 v170, v167, v171
	v_cvt_pk_bf16_f32 v142, v166, v167
	v_add_f32_e32 v143, 1.0, v143
	v_rcp_f32_e32 v172, v143
	v_mul_f32_e32 v143, 0x3d372713, v145
	v_mul_f32_e32 v143, v145, v143
	v_fma_f32 v143, v145, v143, v145
	v_mul_f32_e32 v143, 0x3fcc422a, v143
	v_mul_f32_e32 v143, 0xbfb8aa3b, v143
	v_exp_f32_e32 v143, v143
	v_pk_add_f32 v[168:169], v[176:177], v[168:169] op_sel_hi:[0,1]
	v_add_f32_e32 v143, 1.0, v143
	v_rcp_f32_e32 v173, v143
	s_nop 0
	v_pk_mul_f32 v[174:175], v[144:145], v[172:173]
	s_nop 0
	v_mov_b32_e32 v166, v174
	v_mov_b32_e32 v171, v175
	v_pk_fma_f32 v[166:167], v[166:167], v[166:167], v[168:169]
	v_pk_fma_f32 v[144:145], v[144:145], v[172:173], v[170:171]
	v_pk_mul_f32 v[168:169], v[174:175], v[174:175]
	v_pk_mov_b32 v[166:167], v[174:175], v[166:167] op_sel:[1,0]
	v_mov_b32_e32 v145, v169
	v_pk_add_f32 v[144:145], v[144:145], v[166:167]
	v_cvt_pk_bf16_f32 v143, v174, v175
	global_store_dwordx4 v[138:139], v[140:143], off offset:256
	v_mov_b32_e32 v138, v144
	s_nop 1
	v_permlane16_swap_b32_e32 v138, v144
	v_mov_b32_e32 v139, v145
	s_nop 1
	v_permlane16_swap_b32_e32 v139, v145
	s_waitcnt lgkmcnt(0)
	v_pk_add_f32 v[138:139], v[144:145], v[138:139]
	ds_bpermute_b32 v140, v0, v138
	ds_bpermute_b32 v141, v0, v139
	s_and_saveexec_b64 s[10:11], vcc
	s_cbranch_execz .LBB0_880
	v_lshlrev_b64 v[136:137], 7, v[136:137]
	v_lshl_add_u64 v[136:137], s[0:1], 0, v[136:137]
	s_waitcnt lgkmcnt(0)
	v_pk_add_f32 v[138:139], v[138:139], v[140:141]
	global_store_dwordx2 v[136:137], v[138:139], off
; __device__ __forceinline__ float sigm(float x) { return __builtin_amdgcn_rcpf(1.f + __expf(-x)); }
; __device__ __forceinline__ float gelu_tanh(float x) { return x * sigm(1.5957691216f * (x + 0.044715f * x * x * x)); }
; __device__ __forceinline__ u32x4 pack8(const float* v) { u32x4 w; w.x = cvtpk(v[0], v[1]); w.y = cvtpk(v[2], v[3]); w.z = cvtpk(v[4], v[5]); w.w = cvtpk(v[6], v[7]); return w; }
;     template <int KIND>
;     __device__ __forceinline__ void act_tile(const pg8::f32x4 (&acc)[2][2][4][2], const float (&rs)[2][4], unsigned char* w_, int row0, int colt, int statslot, int fq_) const {
;     ...
;         for (int ai = 0; ai < 2; ++ai)
; #pragma unroll
;             for (int m = 0; m < 4; ++m) {
;                 const int row = row0 + ai * 128 + m * 16;
;                 float s1 = 0.f, s2 = 0.f;
; #pragma unroll
;                 for (int bj = 0; bj < 2; ++bj) {
;                     float v[8];
; #pragma unroll
;                     for (int n = 0; n < 2; ++n)
; #pragma unroll
;                         for (int j = 0; j < 4; ++j) {
;                             const float a = acc[ai][bj][m][n][j] * rs[ai][m];
;                             const float r = KIND == 2 ? sigm(a) : gelu_tanh(a);
;                             v[n * 4 + j] = r;
;                             if (KIND == 1) { s1 += r; s2 += r * r; }
;                         }
;                     *(u32x4*)(base + (size_t)row * ldc + colt + bj * 128) = pack8(v);
;                 }
;                 if (KIND == 1) {
;                     s1 += __shfl_xor(s1, 16); s1 += __shfl_xor(s1, 32); s2 += __shfl_xor(s2, 16); s2 += __shfl_xor(s2, 32);
.LBB0_880:
	s_or_b64 exec, exec, s[10:11]
	s_waitcnt lgkmcnt(0)
	v_pk_mul_f32 v[140:141], v[62:63], v[160:161] op_sel_hi:[1,0]
	v_pk_mul_f32 v[144:145], v[64:65], v[160:161] op_sel_hi:[1,0]
	v_mul_f32_e32 v142, 0x3d372713, v140
	v_mul_f32_e32 v143, 0x3d372713, v141
	v_mul_f32_e32 v142, v140, v142
	v_mul_f32_e32 v143, v141, v143
	v_fma_f32 v142, v140, v142, v140
	v_fma_f32 v143, v141, v143, v141
	v_mul_f32_e32 v166, 0x3d372713, v144
	v_mul_f32_e32 v167, 0x3d372713, v145
	v_mul_f32_e32 v142, 0x3fcc422a, v142
	v_mul_f32_e32 v143, 0x3fcc422a, v143
	v_mul_f32_e32 v166, v144, v166
	v_mul_f32_e32 v167, v145, v167
	v_mul_f32_e32 v142, 0xbfb8aa3b, v142
	v_mul_f32_e32 v143, 0xbfb8aa3b, v143
	v_fma_f32 v166, v144, v166, v144
	v_fma_f32 v167, v145, v167, v145
	v_exp_f32_e32 v142, v142
	v_exp_f32_e32 v143, v143
	v_mul_f32_e32 v166, 0x3fcc422a, v166
	v_mul_f32_e32 v167, 0x3fcc422a, v167
	v_mul_f32_e32 v166, 0xbfb8aa3b, v166
	v_mul_f32_e32 v167, 0xbfb8aa3b, v167
	v_exp_f32_e32 v166, v166
	v_exp_f32_e32 v167, v167
	v_add_f32_e32 v142, 1.0, v142
	v_add_f32_e32 v143, 1.0, v143
	v_rcp_f32_e32 v142, v142
	v_rcp_f32_e32 v143, v143
	v_add_f32_e32 v166, 1.0, v166
	v_add_f32_e32 v167, 1.0, v167
	v_rcp_f32_e32 v166, v166
	v_rcp_f32_e32 v167, v167
	v_pk_mul_f32 v[140:141], v[140:141], v[142:143]
	v_add_u32_e32 v136, 0x80, v158
	v_add_f32_e32 v142, 0, v140
	v_add_f32_e32 v168, v141, v142
	v_pk_mul_f32 v[144:145], v[144:145], v[166:167]
	v_mul_f32_e32 v142, v141, v141
	v_add_f32_e32 v166, v144, v168
	v_add_f32_e32 v170, v145, v166
	v_pk_mul_f32 v[166:167], v[58:59], v[160:161] op_sel_hi:[1,0]
	v_pk_fma_f32 v[142:143], v[140:141], v[140:141], v[142:143] op_sel_hi:[1,1,0]
	v_mul_f32_e32 v168, 0x3d372713, v166
	v_mul_f32_e32 v169, 0x3d372713, v167
	v_mul_f32_e32 v168, v166, v168
	v_mul_f32_e32 v169, v167, v169
	v_fma_f32 v168, v166, v168, v166
	v_fma_f32 v169, v167, v169, v167
	v_mul_f32_e32 v168, 0x3fcc422a, v168
	v_mul_f32_e32 v169, 0x3fcc422a, v169
	v_mul_f32_e32 v168, 0xbfb8aa3b, v168
	v_mul_f32_e32 v169, 0xbfb8aa3b, v169
	v_exp_f32_e32 v168, v168
	v_exp_f32_e32 v169, v169
	v_pk_fma_f32 v[142:143], v[144:145], v[144:145], v[142:143]
	v_ashrrev_i32_e32 v137, 31, v136
	v_add_f32_e32 v168, 1.0, v168
	v_add_f32_e32 v169, 1.0, v169
	v_rcp_f32_e32 v168, v168
	v_rcp_f32_e32 v169, v169
	v_lshlrev_b64 v[138:139], 11, v[136:137]
	v_lshl_add_u64 v[138:139], v[134:135], 0, v[138:139]
	v_cvt_pk_bf16_f32 v140, v140, v141
	v_pk_mul_f32 v[166:167], v[166:167], v[168:169]
	v_mov_b32_e32 v169, v145
	v_add_f32_e32 v171, v166, v170
	v_mul_f32_e32 v170, v145, v145
	v_mov_b32_e32 v168, v166
	v_pk_add_f32 v[142:143], v[170:171], v[142:143] op_sel_hi:[0,1]
	v_pk_fma_f32 v[142:143], v[168:169], v[168:169], v[142:143]
	v_pk_mul_f32 v[168:169], v[60:61], v[160:161] op_sel_hi:[1,0]
	v_add_f32_e32 v172, v167, v171
	v_mul_f32_e32 v170, 0x3d372713, v168
	v_mul_f32_e32 v171, 0x3d372713, v169
	v_mul_f32_e32 v170, v168, v170
	v_mul_f32_e32 v171, v169, v171
	v_fma_f32 v170, v168, v170, v168
	v_fma_f32 v171, v169, v171, v169
	v_mul_f32_e32 v170, 0x3fcc422a, v170
	v_mul_f32_e32 v171, 0x3fcc422a, v171
	v_mul_f32_e32 v170, 0xbfb8aa3b, v170
	v_mul_f32_e32 v171, 0xbfb8aa3b, v171
	v_exp_f32_e32 v170, v170
	v_exp_f32_e32 v171, v171
	v_cvt_pk_bf16_f32 v141, v144, v145
	v_add_f32_e32 v170, 1.0, v170
	v_add_f32_e32 v171, 1.0, v171
	v_rcp_f32_e32 v170, v170
	v_rcp_f32_e32 v171, v171
	s_nop 0
	v_pk_mul_f32 v[168:169], v[168:169], v[170:171]
	s_nop 0
	v_add_f32_e32 v173, v168, v172
	v_mul_f32_e32 v172, v167, v167
	v_mov_b32_e32 v170, v168
	v_mov_b32_e32 v171, v167
	v_pk_add_f32 v[142:143], v[172:173], v[142:143] op_sel_hi:[0,1]
	v_pk_fma_f32 v[170:171], v[170:171], v[170:171], v[142:143]
	v_cvt_pk_bf16_f32 v142, v166, v167
	v_cvt_pk_bf16_f32 v143, v168, v169
	global_store_dwordx4 v[138:139], v[140:143], off
	v_add_f32_e32 v172, v169, v173
	s_nop 0
	v_pk_mul_f32 v[140:141], v[54:55], v[160:161] op_sel_hi:[1,0]
	s_nop 0
	v_mul_f32_e32 v142, 0x3d372713, v140
	v_mul_f32_e32 v143, 0x3d372713, v141
	v_mul_f32_e32 v142, v140, v142
	v_mul_f32_e32 v143, v141, v143
	v_fma_f32 v142, v140, v142, v140
	v_fma_f32 v143, v141, v143, v141
	v_mul_f32_e32 v142, 0x3fcc422a, v142
	v_mul_f32_e32 v143, 0x3fcc422a, v143
	v_mul_f32_e32 v142, 0xbfb8aa3b, v142
	v_mul_f32_e32 v143, 0xbfb8aa3b, v143
	v_exp_f32_e32 v142, v142
	v_exp_f32_e32 v143, v143
	v_add_f32_e32 v142, 1.0, v142
	v_add_f32_e32 v143, 1.0, v143
	v_rcp_f32_e32 v142, v142
	v_rcp_f32_e32 v143, v143
	s_nop 0
	v_pk_mul_f32 v[140:141], v[140:141], v[142:143]
	v_mul_f32_e32 v142, v169, v169
	v_add_f32_e32 v144, v140, v172
	v_mov_b32_e32 v168, v140
	v_pk_add_f32 v[142:143], v[142:143], v[170:171] op_sel_hi:[0,1]
	v_pk_fma_f32 v[142:143], v[168:169], v[168:169], v[142:143]
	v_add_f32_e32 v168, v141, v144
	v_pk_mul_f32 v[144:145], v[56:57], v[160:161] op_sel_hi:[1,0]
	v_cvt_pk_bf16_f32 v140, v140, v141
	v_mul_f32_e32 v166, 0x3d372713, v144
	v_mul_f32_e32 v167, 0x3d372713, v145
	v_mul_f32_e32 v166, v144, v166
	v_mul_f32_e32 v167, v145, v167
	v_fma_f32 v166, v144, v166, v144
	v_fma_f32 v167, v145, v167, v145
	v_mul_f32_e32 v166, 0x3fcc422a, v166
	v_mul_f32_e32 v167, 0x3fcc422a, v167
	v_mul_f32_e32 v166, 0xbfb8aa3b, v166
	v_mul_f32_e32 v167, 0xbfb8aa3b, v167
	v_exp_f32_e32 v166, v166
	v_exp_f32_e32 v167, v167
	v_add_f32_e32 v166, 1.0, v166
	v_add_f32_e32 v167, 1.0, v167
	v_rcp_f32_e32 v166, v166
	v_rcp_f32_e32 v167, v167
	s_nop 0
	v_pk_mul_f32 v[144:145], v[144:145], v[166:167]
	s_nop 0
	v_add_f32_e32 v169, v144, v168
	v_mul_f32_e32 v168, v141, v141
	v_mov_b32_e32 v166, v144
	v_mov_b32_e32 v167, v141
	v_pk_add_f32 v[142:143], v[168:169], v[142:143] op_sel_hi:[0,1]
; __device__ __forceinline__ float sigm(float x) { return __builtin_amdgcn_rcpf(1.f + __expf(-x)); }
; __device__ __forceinline__ float gelu_tanh(float x) { return x * sigm(1.5957691216f * (x + 0.044715f * x * x * x)); }
; __device__ __forceinline__ u32x4 pack8(const float* v) { u32x4 w; w.x = cvtpk(v[0], v[1]); w.y = cvtpk(v[2], v[3]); w.z = cvtpk(v[4], v[5]); w.w = cvtpk(v[6], v[7]); return w; }
;     template <int KIND>
;     __device__ __forceinline__ void act_tile(const pg8::f32x4 (&acc)[2][2][4][2], const float (&rs)[2][4], unsigned char* w_, int row0, int colt, int statslot, int fq_) const {
;     ...
;         for (int ai = 0; ai < 2; ++ai)
; #pragma unroll
;             for (int m = 0; m < 4; ++m) {
;                 const int row = row0 + ai * 128 + m * 16;
;                 float s1 = 0.f, s2 = 0.f;
; #pragma unroll
;                 for (int bj = 0; bj < 2; ++bj) {
;                     float v[8];
; #pragma unroll
;                     for (int n = 0; n < 2; ++n)
; #pragma unroll
;                         for (int j = 0; j < 4; ++j) {
;                             const float a = acc[ai][bj][m][n][j] * rs[ai][m];
;                             const float r = KIND == 2 ? sigm(a) : gelu_tanh(a);
;                             v[n * 4 + j] = r;
;                             if (KIND == 1) { s1 += r; s2 += r * r; }
;                         }
;                     *(u32x4*)(base + (size_t)row * ldc + colt + bj * 128) = pack8(v);
;                 }
;                 if (KIND == 1) {
;                     s1 += __shfl_xor(s1, 16); s1 += __shfl_xor(s1, 32); s2 += __shfl_xor(s2, 16); s2 += __shfl_xor(s2, 32);
;                     if (fq_ == 0) { float* sp = (float*)(w_ + WS_VSTAT) + ((size_t)row * 16 + statslot) * 2; sp[0] = s1; sp[1] = s2; }
;                 }
	v_pk_fma_f32 v[142:143], v[166:167], v[166:167], v[142:143]
	v_pk_mul_f32 v[166:167], v[50:51], v[160:161] op_sel_hi:[1,0]
	v_add_f32_e32 v170, v145, v169
	v_mul_f32_e32 v168, 0x3d372713, v166
	v_mul_f32_e32 v169, 0x3d372713, v167
	v_mul_f32_e32 v168, v166, v168
	v_mul_f32_e32 v169, v167, v169
	v_fma_f32 v168, v166, v168, v166
	v_fma_f32 v169, v167, v169, v167
	v_mul_f32_e32 v168, 0x3fcc422a, v168
	v_mul_f32_e32 v169, 0x3fcc422a, v169
	v_mul_f32_e32 v168, 0xbfb8aa3b, v168
	v_mul_f32_e32 v169, 0xbfb8aa3b, v169
	v_exp_f32_e32 v168, v168
	v_exp_f32_e32 v169, v169
	v_cvt_pk_bf16_f32 v141, v144, v145
	v_add_f32_e32 v168, 1.0, v168
	v_add_f32_e32 v169, 1.0, v169
	v_rcp_f32_e32 v168, v168
	v_rcp_f32_e32 v169, v169
	s_nop 0
	v_pk_mul_f32 v[166:167], v[166:167], v[168:169]
	s_nop 0
	v_add_f32_e32 v171, v166, v170
	v_mul_f32_e32 v170, v145, v145
	v_mov_b32_e32 v168, v166
	v_mov_b32_e32 v169, v145
	v_pk_add_f32 v[142:143], v[170:171], v[142:143] op_sel_hi:[0,1]
	v_pk_mul_f32 v[144:145], v[52:53], v[160:161] op_sel_hi:[1,0]
	v_pk_fma_f32 v[168:169], v[168:169], v[168:169], v[142:143]
	v_mul_f32_e32 v143, 0x3d372713, v144
	v_mul_f32_e32 v143, v144, v143
	v_fma_f32 v143, v144, v143, v144
	v_mul_f32_e32 v143, 0x3fcc422a, v143
	v_mul_f32_e32 v143, 0xbfb8aa3b, v143
	v_exp_f32_e32 v143, v143
	v_mul_f32_e32 v176, v167, v167
	v_add_f32_e32 v170, v167, v171
	v_cvt_pk_bf16_f32 v142, v166, v167
	v_add_f32_e32 v143, 1.0, v143
	v_rcp_f32_e32 v172, v143
	v_mul_f32_e32 v143, 0x3d372713, v145
	v_mul_f32_e32 v143, v145, v143
	v_fma_f32 v143, v145, v143, v145
	v_mul_f32_e32 v143, 0x3fcc422a, v143
	v_mul_f32_e32 v143, 0xbfb8aa3b, v143
	v_exp_f32_e32 v143, v143
	v_pk_add_f32 v[168:169], v[176:177], v[168:169] op_sel_hi:[0,1]
	v_add_f32_e32 v143, 1.0, v143
	v_rcp_f32_e32 v173, v143
	s_nop 0
	v_pk_mul_f32 v[174:175], v[144:145], v[172:173]
	s_nop 0
	v_mov_b32_e32 v166, v174
	v_mov_b32_e32 v171, v175
	v_pk_fma_f32 v[166:167], v[166:167], v[166:167], v[168:169]
	v_pk_fma_f32 v[144:145], v[144:145], v[172:173], v[170:171]
	v_pk_mul_f32 v[168:169], v[174:175], v[174:175]
	v_pk_mov_b32 v[166:167], v[174:175], v[166:167] op_sel:[1,0]
	v_mov_b32_e32 v145, v169
	v_pk_add_f32 v[144:145], v[144:145], v[166:167]
	v_cvt_pk_bf16_f32 v143, v174, v175
	global_store_dwordx4 v[138:139], v[140:143], off offset:256
	v_mov_b32_e32 v138, v144
	s_nop 1
	v_permlane16_swap_b32_e32 v138, v144
	v_mov_b32_e32 v139, v145
	s_nop 1
	v_permlane16_swap_b32_e32 v139, v145
	s_waitcnt lgkmcnt(0)
	v_pk_add_f32 v[138:139], v[144:145], v[138:139]
	ds_bpermute_b32 v140, v0, v138
	ds_bpermute_b32 v141, v0, v139
	s_and_saveexec_b64 s[10:11], vcc
	s_cbranch_execz .LBB0_882
	v_lshlrev_b64 v[136:137], 7, v[136:137]
	v_lshl_add_u64 v[136:137], s[0:1], 0, v[136:137]
	s_waitcnt lgkmcnt(0)
	v_pk_add_f32 v[138:139], v[138:139], v[140:141]
	global_store_dwordx2 v[136:137], v[138:139], off
.LBB0_882:
	s_or_b64 exec, exec, s[10:11]
	s_waitcnt lgkmcnt(0)
	v_pk_mul_f32 v[140:141], v[46:47], v[160:161] op_sel:[0,1]
	v_pk_mul_f32 v[144:145], v[48:49], v[160:161] op_sel:[0,1]
	v_mul_f32_e32 v142, 0x3d372713, v140
	v_mul_f32_e32 v143, 0x3d372713, v141
	v_mul_f32_e32 v142, v140, v142
	v_mul_f32_e32 v143, v141, v143
	v_fma_f32 v142, v140, v142, v140
	v_fma_f32 v143, v141, v143, v141
	v_mul_f32_e32 v166, 0x3d372713, v144
	v_mul_f32_e32 v167, 0x3d372713, v145
	v_mul_f32_e32 v142, 0x3fcc422a, v142
	v_mul_f32_e32 v143, 0x3fcc422a, v143
	v_mul_f32_e32 v166, v144, v166
	v_mul_f32_e32 v167, v145, v167
	v_mul_f32_e32 v142, 0xbfb8aa3b, v142
	v_mul_f32_e32 v143, 0xbfb8aa3b, v143
	v_fma_f32 v166, v144, v166, v144
	v_fma_f32 v167, v145, v167, v145
	v_exp_f32_e32 v142, v142
	v_exp_f32_e32 v143, v143
	v_mul_f32_e32 v166, 0x3fcc422a, v166
	v_mul_f32_e32 v167, 0x3fcc422a, v167
	v_mul_f32_e32 v166, 0xbfb8aa3b, v166
	v_mul_f32_e32 v167, 0xbfb8aa3b, v167
	v_exp_f32_e32 v166, v166
	v_exp_f32_e32 v167, v167
	v_add_f32_e32 v142, 1.0, v142
	v_add_f32_e32 v143, 1.0, v143
	v_rcp_f32_e32 v142, v142
	v_rcp_f32_e32 v143, v143
	v_add_f32_e32 v166, 1.0, v166
	v_add_f32_e32 v167, 1.0, v167
	v_rcp_f32_e32 v166, v166
	v_rcp_f32_e32 v167, v167
	v_pk_mul_f32 v[140:141], v[140:141], v[142:143]
	v_add_u32_e32 v136, 0x90, v158
	v_add_f32_e32 v142, 0, v140
	v_add_f32_e32 v168, v141, v142
	v_pk_mul_f32 v[144:145], v[144:145], v[166:167]
	v_mul_f32_e32 v142, v141, v141
	v_add_f32_e32 v166, v144, v168
	v_add_f32_e32 v170, v145, v166
	v_pk_mul_f32 v[166:167], v[42:43], v[160:161] op_sel:[0,1]
	v_pk_fma_f32 v[142:143], v[140:141], v[140:141], v[142:143] op_sel_hi:[1,1,0]
	v_mul_f32_e32 v168, 0x3d372713, v166
	v_mul_f32_e32 v169, 0x3d372713, v167
	v_mul_f32_e32 v168, v166, v168
	v_mul_f32_e32 v169, v167, v169
	v_fma_f32 v168, v166, v168, v166
	v_fma_f32 v169, v167, v169, v167
	v_mul_f32_e32 v168, 0x3fcc422a, v168
	v_mul_f32_e32 v169, 0x3fcc422a, v169
	v_mul_f32_e32 v168, 0xbfb8aa3b, v168
	v_mul_f32_e32 v169, 0xbfb8aa3b, v169
	v_exp_f32_e32 v168, v168
	v_exp_f32_e32 v169, v169
	v_pk_fma_f32 v[142:143], v[144:145], v[144:145], v[142:143]
	v_ashrrev_i32_e32 v137, 31, v136
	v_add_f32_e32 v168, 1.0, v168
	v_add_f32_e32 v169, 1.0, v169
	v_rcp_f32_e32 v168, v168
	v_rcp_f32_e32 v169, v169
	v_lshlrev_b64 v[138:139], 11, v[136:137]
	v_lshl_add_u64 v[138:139], v[134:135], 0, v[138:139]
	v_cvt_pk_bf16_f32 v140, v140, v141
	v_pk_mul_f32 v[166:167], v[166:167], v[168:169]
	v_mov_b32_e32 v169, v145
	v_add_f32_e32 v171, v166, v170
	v_mul_f32_e32 v170, v145, v145
	v_mov_b32_e32 v168, v166
	v_pk_add_f32 v[142:143], v[170:171], v[142:143] op_sel_hi:[0,1]
	v_pk_fma_f32 v[142:143], v[168:169], v[168:169], v[142:143]
	v_pk_mul_f32 v[168:169], v[44:45], v[160:161] op_sel:[0,1]
; __device__ __forceinline__ float sigm(float x) { return __builtin_amdgcn_rcpf(1.f + __expf(-x)); }
; __device__ __forceinline__ float gelu_tanh(float x) { return x * sigm(1.5957691216f * (x + 0.044715f * x * x * x)); }
; __device__ __forceinline__ u32x4 pack8(const float* v) { u32x4 w; w.x = cvtpk(v[0], v[1]); w.y = cvtpk(v[2], v[3]); w.z = cvtpk(v[4], v[5]); w.w = cvtpk(v[6], v[7]); return w; }
;     template <int KIND>
;     __device__ __forceinline__ void act_tile(const pg8::f32x4 (&acc)[2][2][4][2], const float (&rs)[2][4], unsigned char* w_, int row0, int colt, int statslot, int fq_) const {
;     ...
;         for (int ai = 0; ai < 2; ++ai)
; #pragma unroll
;             for (int m = 0; m < 4; ++m) {
;                 const int row = row0 + ai * 128 + m * 16;
;                 float s1 = 0.f, s2 = 0.f;
; #pragma unroll
;                 for (int bj = 0; bj < 2; ++bj) {
;                     float v[8];
; #pragma unroll
;                     for (int n = 0; n < 2; ++n)
; #pragma unroll
;                         for (int j = 0; j < 4; ++j) {
;                             const float a = acc[ai][bj][m][n][j] * rs[ai][m];
;                             const float r = KIND == 2 ? sigm(a) : gelu_tanh(a);
;                             v[n * 4 + j] = r;
;                             if (KIND == 1) { s1 += r; s2 += r * r; }
;                         }
;                     *(u32x4*)(base + (size_t)row * ldc + colt + bj * 128) = pack8(v);
;                 }
;                 if (KIND == 1) {
;                     s1 += __shfl_xor(s1, 16); s1 += __shfl_xor(s1, 32); s2 += __shfl_xor(s2, 16); s2 += __shfl_xor(s2, 32);
;                     if (fq_ == 0) { float* sp = (float*)(w_ + WS_VSTAT) + ((size_t)row * 16 + statslot) * 2; sp[0] = s1; sp[1] = s2; }
;                 }
	v_add_f32_e32 v172, v167, v171
	v_mul_f32_e32 v170, 0x3d372713, v168
	v_mul_f32_e32 v171, 0x3d372713, v169
	v_mul_f32_e32 v170, v168, v170
	v_mul_f32_e32 v171, v169, v171
	v_fma_f32 v170, v168, v170, v168
	v_fma_f32 v171, v169, v171, v169
	v_mul_f32_e32 v170, 0x3fcc422a, v170
	v_mul_f32_e32 v171, 0x3fcc422a, v171
	v_mul_f32_e32 v170, 0xbfb8aa3b, v170
	v_mul_f32_e32 v171, 0xbfb8aa3b, v171
	v_exp_f32_e32 v170, v170
	v_exp_f32_e32 v171, v171
	v_cvt_pk_bf16_f32 v141, v144, v145
	v_add_f32_e32 v170, 1.0, v170
	v_add_f32_e32 v171, 1.0, v171
	v_rcp_f32_e32 v170, v170
	v_rcp_f32_e32 v171, v171
	s_nop 0
	v_pk_mul_f32 v[168:169], v[168:169], v[170:171]
	s_nop 0
	v_add_f32_e32 v173, v168, v172
	v_mul_f32_e32 v172, v167, v167
	v_mov_b32_e32 v170, v168
	v_mov_b32_e32 v171, v167
	v_pk_add_f32 v[142:143], v[172:173], v[142:143] op_sel_hi:[0,1]
	v_pk_fma_f32 v[170:171], v[170:171], v[170:171], v[142:143]
	v_cvt_pk_bf16_f32 v142, v166, v167
	v_cvt_pk_bf16_f32 v143, v168, v169
	global_store_dwordx4 v[138:139], v[140:143], off
	v_add_f32_e32 v172, v169, v173
	s_nop 0
	v_pk_mul_f32 v[140:141], v[38:39], v[160:161] op_sel:[0,1]
	s_nop 0
	v_mul_f32_e32 v142, 0x3d372713, v140
	v_mul_f32_e32 v143, 0x3d372713, v141
	v_mul_f32_e32 v142, v140, v142
	v_mul_f32_e32 v143, v141, v143
	v_fma_f32 v142, v140, v142, v140
	v_fma_f32 v143, v141, v143, v141
	v_mul_f32_e32 v142, 0x3fcc422a, v142
	v_mul_f32_e32 v143, 0x3fcc422a, v143
	v_mul_f32_e32 v142, 0xbfb8aa3b, v142
	v_mul_f32_e32 v143, 0xbfb8aa3b, v143
	v_exp_f32_e32 v142, v142
	v_exp_f32_e32 v143, v143
	v_add_f32_e32 v142, 1.0, v142
	v_add_f32_e32 v143, 1.0, v143
	v_rcp_f32_e32 v142, v142
	v_rcp_f32_e32 v143, v143
	s_nop 0
	v_pk_mul_f32 v[140:141], v[140:141], v[142:143]
	v_mul_f32_e32 v142, v169, v169
	v_add_f32_e32 v144, v140, v172
	v_mov_b32_e32 v168, v140
	v_pk_add_f32 v[142:143], v[142:143], v[170:171] op_sel_hi:[0,1]
	v_pk_fma_f32 v[142:143], v[168:169], v[168:169], v[142:143]
	v_add_f32_e32 v168, v141, v144
	v_pk_mul_f32 v[144:145], v[40:41], v[160:161] op_sel:[0,1]
	v_cvt_pk_bf16_f32 v140, v140, v141
	v_mul_f32_e32 v166, 0x3d372713, v144
	v_mul_f32_e32 v167, 0x3d372713, v145
	v_mul_f32_e32 v166, v144, v166
	v_mul_f32_e32 v167, v145, v167
	v_fma_f32 v166, v144, v166, v144
	v_fma_f32 v167, v145, v167, v145
	v_mul_f32_e32 v166, 0x3fcc422a, v166
	v_mul_f32_e32 v167, 0x3fcc422a, v167
	v_mul_f32_e32 v166, 0xbfb8aa3b, v166
	v_mul_f32_e32 v167, 0xbfb8aa3b, v167
	v_exp_f32_e32 v166, v166
	v_exp_f32_e32 v167, v167
	v_add_f32_e32 v166, 1.0, v166
	v_add_f32_e32 v167, 1.0, v167
	v_rcp_f32_e32 v166, v166
	v_rcp_f32_e32 v167, v167
	s_nop 0
	v_pk_mul_f32 v[144:145], v[144:145], v[166:167]
	s_nop 0
	v_add_f32_e32 v169, v144, v168
	v_mul_f32_e32 v168, v141, v141
	v_mov_b32_e32 v166, v144
	v_mov_b32_e32 v167, v141
	v_pk_add_f32 v[142:143], v[168:169], v[142:143] op_sel_hi:[0,1]
	v_pk_fma_f32 v[142:143], v[166:167], v[166:167], v[142:143]
	v_pk_mul_f32 v[166:167], v[34:35], v[160:161] op_sel:[0,1]
	v_add_f32_e32 v170, v145, v169
	v_mul_f32_e32 v168, 0x3d372713, v166
	v_mul_f32_e32 v169, 0x3d372713, v167
	v_mul_f32_e32 v168, v166, v168
	v_mul_f32_e32 v169, v167, v169
	v_fma_f32 v168, v166, v168, v166
	v_fma_f32 v169, v167, v169, v167
	v_mul_f32_e32 v168, 0x3fcc422a, v168
	v_mul_f32_e32 v169, 0x3fcc422a, v169
	v_mul_f32_e32 v168, 0xbfb8aa3b, v168
	v_mul_f32_e32 v169, 0xbfb8aa3b, v169
	v_exp_f32_e32 v168, v168
	v_exp_f32_e32 v169, v169
	v_cvt_pk_bf16_f32 v141, v144, v145
	v_add_f32_e32 v168, 1.0, v168
	v_add_f32_e32 v169, 1.0, v169
	v_rcp_f32_e32 v168, v168
	v_rcp_f32_e32 v169, v169
	s_nop 0
	v_pk_mul_f32 v[166:167], v[166:167], v[168:169]
	s_nop 0
	v_add_f32_e32 v171, v166, v170
	v_mul_f32_e32 v170, v145, v145
	v_mov_b32_e32 v168, v166
	v_mov_b32_e32 v169, v145
	v_pk_add_f32 v[142:143], v[170:171], v[142:143] op_sel_hi:[0,1]
	v_pk_mul_f32 v[144:145], v[36:37], v[160:161] op_sel:[0,1]
	v_pk_fma_f32 v[168:169], v[168:169], v[168:169], v[142:143]
	v_mul_f32_e32 v143, 0x3d372713, v144
	v_mul_f32_e32 v143, v144, v143
	v_fma_f32 v143, v144, v143, v144
	v_mul_f32_e32 v143, 0x3fcc422a, v143
	v_mul_f32_e32 v143, 0xbfb8aa3b, v143
	v_exp_f32_e32 v143, v143
	v_mul_f32_e32 v176, v167, v167
	v_add_f32_e32 v170, v167, v171
	v_cvt_pk_bf16_f32 v142, v166, v167
	v_add_f32_e32 v143, 1.0, v143
	v_rcp_f32_e32 v172, v143
	v_mul_f32_e32 v143, 0x3d372713, v145
	v_mul_f32_e32 v143, v145, v143
	v_fma_f32 v143, v145, v143, v145
	v_mul_f32_e32 v143, 0x3fcc422a, v143
	v_mul_f32_e32 v143, 0xbfb8aa3b, v143
	v_exp_f32_e32 v143, v143
	v_pk_add_f32 v[168:169], v[176:177], v[168:169] op_sel_hi:[0,1]
	v_add_f32_e32 v143, 1.0, v143
	v_rcp_f32_e32 v173, v143
	s_nop 0
	v_pk_mul_f32 v[174:175], v[144:145], v[172:173]
	s_nop 0
	v_mov_b32_e32 v166, v174
	v_mov_b32_e32 v171, v175
	v_pk_fma_f32 v[166:167], v[166:167], v[166:167], v[168:169]
	v_pk_fma_f32 v[144:145], v[144:145], v[172:173], v[170:171]
	v_pk_mul_f32 v[168:169], v[174:175], v[174:175]
	v_pk_mov_b32 v[166:167], v[174:175], v[166:167] op_sel:[1,0]
	v_mov_b32_e32 v145, v169
	v_pk_add_f32 v[144:145], v[144:145], v[166:167]
	v_cvt_pk_bf16_f32 v143, v174, v175
	global_store_dwordx4 v[138:139], v[140:143], off offset:256
	v_mov_b32_e32 v138, v144
	s_nop 1
	v_permlane16_swap_b32_e32 v138, v144
	v_mov_b32_e32 v139, v145
	s_nop 1
	v_permlane16_swap_b32_e32 v139, v145
	s_waitcnt lgkmcnt(0)
	v_pk_add_f32 v[138:139], v[144:145], v[138:139]
	ds_bpermute_b32 v140, v0, v138
	ds_bpermute_b32 v141, v0, v139
	s_and_saveexec_b64 s[10:11], vcc
	s_cbranch_execz .LBB0_884
	v_lshlrev_b64 v[136:137], 7, v[136:137]
	v_lshl_add_u64 v[136:137], s[0:1], 0, v[136:137]
	s_waitcnt lgkmcnt(0)
	v_pk_add_f32 v[138:139], v[138:139], v[140:141]
	global_store_dwordx2 v[136:137], v[138:139], off
; __device__ __forceinline__ float sigm(float x) { return __builtin_amdgcn_rcpf(1.f + __expf(-x)); }
; __device__ __forceinline__ float gelu_tanh(float x) { return x * sigm(1.5957691216f * (x + 0.044715f * x * x * x)); }
; __device__ __forceinline__ u32x4 pack8(const float* v) { u32x4 w; w.x = cvtpk(v[0], v[1]); w.y = cvtpk(v[2], v[3]); w.z = cvtpk(v[4], v[5]); w.w = cvtpk(v[6], v[7]); return w; }
;     template <int KIND>
;     __device__ __forceinline__ void act_tile(const pg8::f32x4 (&acc)[2][2][4][2], const float (&rs)[2][4], unsigned char* w_, int row0, int colt, int statslot, int fq_) const {
;     ...
;         for (int ai = 0; ai < 2; ++ai)
; #pragma unroll
;             for (int m = 0; m < 4; ++m) {
;                 const int row = row0 + ai * 128 + m * 16;
;                 float s1 = 0.f, s2 = 0.f;
; #pragma unroll
;                 for (int bj = 0; bj < 2; ++bj) {
;                     float v[8];
; #pragma unroll
;                     for (int n = 0; n < 2; ++n)
; #pragma unroll
;                         for (int j = 0; j < 4; ++j) {
;                             const float a = acc[ai][bj][m][n][j] * rs[ai][m];
;                             const float r = KIND == 2 ? sigm(a) : gelu_tanh(a);
;                             v[n * 4 + j] = r;
;                             if (KIND == 1) { s1 += r; s2 += r * r; }
;                         }
;                     *(u32x4*)(base + (size_t)row * ldc + colt + bj * 128) = pack8(v);
;                 }
;                 if (KIND == 1) {
;                     s1 += __shfl_xor(s1, 16); s1 += __shfl_xor(s1, 32); s2 += __shfl_xor(s2, 16); s2 += __shfl_xor(s2, 32);
.LBB0_884:
	s_or_b64 exec, exec, s[10:11]
	s_waitcnt lgkmcnt(0)
	v_pk_mul_f32 v[140:141], v[30:31], v[132:133] op_sel_hi:[1,0]
	v_pk_mul_f32 v[144:145], v[32:33], v[132:133] op_sel_hi:[1,0]
	v_mul_f32_e32 v142, 0x3d372713, v140
	v_mul_f32_e32 v143, 0x3d372713, v141
	v_mul_f32_e32 v142, v140, v142
	v_mul_f32_e32 v143, v141, v143
	v_fma_f32 v142, v140, v142, v140
	v_fma_f32 v143, v141, v143, v141
	v_mul_f32_e32 v166, 0x3d372713, v144
	v_mul_f32_e32 v167, 0x3d372713, v145
	v_mul_f32_e32 v142, 0x3fcc422a, v142
	v_mul_f32_e32 v143, 0x3fcc422a, v143
	v_mul_f32_e32 v166, v144, v166
	v_mul_f32_e32 v167, v145, v167
	v_mul_f32_e32 v142, 0xbfb8aa3b, v142
	v_mul_f32_e32 v143, 0xbfb8aa3b, v143
	v_fma_f32 v166, v144, v166, v144
	v_fma_f32 v167, v145, v167, v145
	v_exp_f32_e32 v142, v142
	v_exp_f32_e32 v143, v143
	v_mul_f32_e32 v166, 0x3fcc422a, v166
	v_mul_f32_e32 v167, 0x3fcc422a, v167
	v_mul_f32_e32 v166, 0xbfb8aa3b, v166
	v_mul_f32_e32 v167, 0xbfb8aa3b, v167
	v_exp_f32_e32 v166, v166
	v_exp_f32_e32 v167, v167
	v_add_f32_e32 v142, 1.0, v142
	v_add_f32_e32 v143, 1.0, v143
	v_rcp_f32_e32 v142, v142
	v_rcp_f32_e32 v143, v143
	v_add_f32_e32 v166, 1.0, v166
	v_add_f32_e32 v167, 1.0, v167
	v_rcp_f32_e32 v166, v166
	v_rcp_f32_e32 v167, v167
	v_pk_mul_f32 v[140:141], v[140:141], v[142:143]
	v_add_u32_e32 v136, 0xa0, v158
	v_add_f32_e32 v142, 0, v140
	v_add_f32_e32 v168, v141, v142
	v_pk_mul_f32 v[144:145], v[144:145], v[166:167]
	v_mul_f32_e32 v142, v141, v141
	v_add_f32_e32 v166, v144, v168
	v_add_f32_e32 v170, v145, v166
	v_pk_mul_f32 v[166:167], v[26:27], v[132:133] op_sel_hi:[1,0]
	v_pk_fma_f32 v[142:143], v[140:141], v[140:141], v[142:143] op_sel_hi:[1,1,0]
	v_mul_f32_e32 v168, 0x3d372713, v166
	v_mul_f32_e32 v169, 0x3d372713, v167
	v_mul_f32_e32 v168, v166, v168
	v_mul_f32_e32 v169, v167, v169
	v_fma_f32 v168, v166, v168, v166
	v_fma_f32 v169, v167, v169, v167
	v_mul_f32_e32 v168, 0x3fcc422a, v168
	v_mul_f32_e32 v169, 0x3fcc422a, v169
	v_mul_f32_e32 v168, 0xbfb8aa3b, v168
	v_mul_f32_e32 v169, 0xbfb8aa3b, v169
	v_exp_f32_e32 v168, v168
	v_exp_f32_e32 v169, v169
	v_pk_fma_f32 v[142:143], v[144:145], v[144:145], v[142:143]
	v_ashrrev_i32_e32 v137, 31, v136
	v_add_f32_e32 v168, 1.0, v168
	v_add_f32_e32 v169, 1.0, v169
	v_rcp_f32_e32 v168, v168
	v_rcp_f32_e32 v169, v169
	v_lshlrev_b64 v[138:139], 11, v[136:137]
	v_lshl_add_u64 v[138:139], v[134:135], 0, v[138:139]
	v_cvt_pk_bf16_f32 v140, v140, v141
	v_pk_mul_f32 v[166:167], v[166:167], v[168:169]
	v_mov_b32_e32 v169, v145
	v_add_f32_e32 v171, v166, v170
	v_mul_f32_e32 v170, v145, v145
	v_mov_b32_e32 v168, v166
	v_pk_add_f32 v[142:143], v[170:171], v[142:143] op_sel_hi:[0,1]
	v_pk_fma_f32 v[142:143], v[168:169], v[168:169], v[142:143]
	v_pk_mul_f32 v[168:169], v[28:29], v[132:133] op_sel_hi:[1,0]
	v_add_f32_e32 v172, v167, v171
	v_mul_f32_e32 v170, 0x3d372713, v168
	v_mul_f32_e32 v171, 0x3d372713, v169
	v_mul_f32_e32 v170, v168, v170
	v_mul_f32_e32 v171, v169, v171
	v_fma_f32 v170, v168, v170, v168
	v_fma_f32 v171, v169, v171, v169
	v_mul_f32_e32 v170, 0x3fcc422a, v170
	v_mul_f32_e32 v171, 0x3fcc422a, v171
	v_mul_f32_e32 v170, 0xbfb8aa3b, v170
	v_mul_f32_e32 v171, 0xbfb8aa3b, v171
	v_exp_f32_e32 v170, v170
	v_exp_f32_e32 v171, v171
	v_cvt_pk_bf16_f32 v141, v144, v145
	v_add_f32_e32 v170, 1.0, v170
	v_add_f32_e32 v171, 1.0, v171
	v_rcp_f32_e32 v170, v170
	v_rcp_f32_e32 v171, v171
	s_nop 0
	v_pk_mul_f32 v[168:169], v[168:169], v[170:171]
	s_nop 0
	v_add_f32_e32 v173, v168, v172
	v_mul_f32_e32 v172, v167, v167
	v_mov_b32_e32 v170, v168
	v_mov_b32_e32 v171, v167
	v_pk_add_f32 v[142:143], v[172:173], v[142:143] op_sel_hi:[0,1]
	v_pk_fma_f32 v[170:171], v[170:171], v[170:171], v[142:143]
	v_cvt_pk_bf16_f32 v142, v166, v167
	v_cvt_pk_bf16_f32 v143, v168, v169
	global_store_dwordx4 v[138:139], v[140:143], off
	v_add_f32_e32 v172, v169, v173
	s_nop 0
	v_pk_mul_f32 v[140:141], v[22:23], v[132:133] op_sel_hi:[1,0]
	s_nop 0
	v_mul_f32_e32 v142, 0x3d372713, v140
	v_mul_f32_e32 v143, 0x3d372713, v141
	v_mul_f32_e32 v142, v140, v142
	v_mul_f32_e32 v143, v141, v143
	v_fma_f32 v142, v140, v142, v140
	v_fma_f32 v143, v141, v143, v141
	v_mul_f32_e32 v142, 0x3fcc422a, v142
	v_mul_f32_e32 v143, 0x3fcc422a, v143
	v_mul_f32_e32 v142, 0xbfb8aa3b, v142
	v_mul_f32_e32 v143, 0xbfb8aa3b, v143
	v_exp_f32_e32 v142, v142
	v_exp_f32_e32 v143, v143
	v_add_f32_e32 v142, 1.0, v142
	v_add_f32_e32 v143, 1.0, v143
	v_rcp_f32_e32 v142, v142
	v_rcp_f32_e32 v143, v143
	s_nop 0
	v_pk_mul_f32 v[140:141], v[140:141], v[142:143]
	v_mul_f32_e32 v142, v169, v169
	v_add_f32_e32 v144, v140, v172
	v_mov_b32_e32 v168, v140
	v_pk_add_f32 v[142:143], v[142:143], v[170:171] op_sel_hi:[0,1]
	v_pk_fma_f32 v[142:143], v[168:169], v[168:169], v[142:143]
	v_add_f32_e32 v168, v141, v144
	v_pk_mul_f32 v[144:145], v[24:25], v[132:133] op_sel_hi:[1,0]
	v_cvt_pk_bf16_f32 v140, v140, v141
	v_mul_f32_e32 v166, 0x3d372713, v144
	v_mul_f32_e32 v167, 0x3d372713, v145
	v_mul_f32_e32 v166, v144, v166
	v_mul_f32_e32 v167, v145, v167
	v_fma_f32 v166, v144, v166, v144
	v_fma_f32 v167, v145, v167, v145
	v_mul_f32_e32 v166, 0x3fcc422a, v166
	v_mul_f32_e32 v167, 0x3fcc422a, v167
	v_mul_f32_e32 v166, 0xbfb8aa3b, v166
	v_mul_f32_e32 v167, 0xbfb8aa3b, v167
	v_exp_f32_e32 v166, v166
	v_exp_f32_e32 v167, v167
	v_add_f32_e32 v166, 1.0, v166
	v_add_f32_e32 v167, 1.0, v167
	v_rcp_f32_e32 v166, v166
	v_rcp_f32_e32 v167, v167
	s_nop 0
	v_pk_mul_f32 v[144:145], v[144:145], v[166:167]
	s_nop 0
	v_add_f32_e32 v169, v144, v168
	v_mul_f32_e32 v168, v141, v141
	v_mov_b32_e32 v166, v144
	v_mov_b32_e32 v167, v141
	v_pk_add_f32 v[142:143], v[168:169], v[142:143] op_sel_hi:[0,1]
; __device__ __forceinline__ float sigm(float x) { return __builtin_amdgcn_rcpf(1.f + __expf(-x)); }
; __device__ __forceinline__ float gelu_tanh(float x) { return x * sigm(1.5957691216f * (x + 0.044715f * x * x * x)); }
; __device__ __forceinline__ u32x4 pack8(const float* v) { u32x4 w; w.x = cvtpk(v[0], v[1]); w.y = cvtpk(v[2], v[3]); w.z = cvtpk(v[4], v[5]); w.w = cvtpk(v[6], v[7]); return w; }
;     template <int KIND>
;     __device__ __forceinline__ void act_tile(const pg8::f32x4 (&acc)[2][2][4][2], const float (&rs)[2][4], unsigned char* w_, int row0, int colt, int statslot, int fq_) const {
;     ...
;         for (int ai = 0; ai < 2; ++ai)
; #pragma unroll
;             for (int m = 0; m < 4; ++m) {
;                 const int row = row0 + ai * 128 + m * 16;
;                 float s1 = 0.f, s2 = 0.f;
; #pragma unroll
;                 for (int bj = 0; bj < 2; ++bj) {
;                     float v[8];
; #pragma unroll
;                     for (int n = 0; n < 2; ++n)
; #pragma unroll
;                         for (int j = 0; j < 4; ++j) {
;                             const float a = acc[ai][bj][m][n][j] * rs[ai][m];
;                             const float r = KIND == 2 ? sigm(a) : gelu_tanh(a);
;                             v[n * 4 + j] = r;
;                             if (KIND == 1) { s1 += r; s2 += r * r; }
;                         }
;                     *(u32x4*)(base + (size_t)row * ldc + colt + bj * 128) = pack8(v);
;                 }
;                 if (KIND == 1) {
;                     s1 += __shfl_xor(s1, 16); s1 += __shfl_xor(s1, 32); s2 += __shfl_xor(s2, 16); s2 += __shfl_xor(s2, 32);
;                     if (fq_ == 0) { float* sp = (float*)(w_ + WS_VSTAT) + ((size_t)row * 16 + statslot) * 2; sp[0] = s1; sp[1] = s2; }
;                 }
	v_pk_fma_f32 v[142:143], v[166:167], v[166:167], v[142:143]
	v_pk_mul_f32 v[166:167], v[18:19], v[132:133] op_sel_hi:[1,0]
	v_add_f32_e32 v170, v145, v169
	v_mul_f32_e32 v168, 0x3d372713, v166
	v_mul_f32_e32 v169, 0x3d372713, v167
	v_mul_f32_e32 v168, v166, v168
	v_mul_f32_e32 v169, v167, v169
	v_fma_f32 v168, v166, v168, v166
	v_fma_f32 v169, v167, v169, v167
	v_mul_f32_e32 v168, 0x3fcc422a, v168
	v_mul_f32_e32 v169, 0x3fcc422a, v169
	v_mul_f32_e32 v168, 0xbfb8aa3b, v168
	v_mul_f32_e32 v169, 0xbfb8aa3b, v169
	v_exp_f32_e32 v168, v168
	v_exp_f32_e32 v169, v169
	v_cvt_pk_bf16_f32 v141, v144, v145
	v_add_f32_e32 v168, 1.0, v168
	v_add_f32_e32 v169, 1.0, v169
	v_rcp_f32_e32 v168, v168
	v_rcp_f32_e32 v169, v169
	s_nop 0
	v_pk_mul_f32 v[166:167], v[166:167], v[168:169]
	s_nop 0
	v_add_f32_e32 v171, v166, v170
	v_mul_f32_e32 v170, v145, v145
	v_mov_b32_e32 v168, v166
	v_mov_b32_e32 v169, v145
	v_pk_add_f32 v[142:143], v[170:171], v[142:143] op_sel_hi:[0,1]
	v_pk_mul_f32 v[144:145], v[20:21], v[132:133] op_sel_hi:[1,0]
	v_pk_fma_f32 v[168:169], v[168:169], v[168:169], v[142:143]
	v_mul_f32_e32 v143, 0x3d372713, v144
	v_mul_f32_e32 v143, v144, v143
	v_fma_f32 v143, v144, v143, v144
	v_mul_f32_e32 v143, 0x3fcc422a, v143
	v_mul_f32_e32 v143, 0xbfb8aa3b, v143
	v_exp_f32_e32 v143, v143
	v_mul_f32_e32 v176, v167, v167
	v_add_f32_e32 v170, v167, v171
	v_cvt_pk_bf16_f32 v142, v166, v167
	v_add_f32_e32 v143, 1.0, v143
	v_rcp_f32_e32 v172, v143
	v_mul_f32_e32 v143, 0x3d372713, v145
	v_mul_f32_e32 v143, v145, v143
	v_fma_f32 v143, v145, v143, v145
	v_mul_f32_e32 v143, 0x3fcc422a, v143
	v_mul_f32_e32 v143, 0xbfb8aa3b, v143
	v_exp_f32_e32 v143, v143
	v_pk_add_f32 v[168:169], v[176:177], v[168:169] op_sel_hi:[0,1]
	v_add_f32_e32 v143, 1.0, v143
	v_rcp_f32_e32 v173, v143
	s_nop 0
	v_pk_mul_f32 v[174:175], v[144:145], v[172:173]
	s_nop 0
	v_mov_b32_e32 v166, v174
	v_mov_b32_e32 v171, v175
	v_pk_fma_f32 v[166:167], v[166:167], v[166:167], v[168:169]
	v_pk_fma_f32 v[144:145], v[144:145], v[172:173], v[170:171]
	v_pk_mul_f32 v[168:169], v[174:175], v[174:175]
	v_pk_mov_b32 v[166:167], v[174:175], v[166:167] op_sel:[1,0]
	v_mov_b32_e32 v145, v169
	v_pk_add_f32 v[144:145], v[144:145], v[166:167]
	v_cvt_pk_bf16_f32 v143, v174, v175
	global_store_dwordx4 v[138:139], v[140:143], off offset:256
	v_mov_b32_e32 v138, v144
	s_nop 1
	v_permlane16_swap_b32_e32 v138, v144
	v_mov_b32_e32 v139, v145
	s_nop 1
	v_permlane16_swap_b32_e32 v139, v145
	s_waitcnt lgkmcnt(0)
	v_pk_add_f32 v[138:139], v[144:145], v[138:139]
	ds_bpermute_b32 v140, v0, v138
	ds_bpermute_b32 v141, v0, v139
	s_and_saveexec_b64 s[10:11], vcc
	s_cbranch_execz .LBB0_886
	v_lshlrev_b64 v[136:137], 7, v[136:137]
	v_lshl_add_u64 v[136:137], s[0:1], 0, v[136:137]
	s_waitcnt lgkmcnt(0)
	v_pk_add_f32 v[138:139], v[138:139], v[140:141]
	global_store_dwordx2 v[136:137], v[138:139], off
.LBB0_886:
	s_or_b64 exec, exec, s[10:11]
	v_add_u32_e32 v136, 0xb0, v158
	v_ashrrev_i32_e32 v137, 31, v136
	v_lshlrev_b64 v[138:139], 11, v[136:137]
	v_lshl_add_u64 v[134:135], v[134:135], 0, v[138:139]
	v_pk_mul_f32 v[138:139], v[14:15], v[132:133] op_sel:[0,1]
	v_pk_mul_f32 v[142:143], v[16:17], v[132:133] op_sel:[0,1]
	s_waitcnt lgkmcnt(0)
	v_mul_f32_e32 v140, 0x3d372713, v138
	v_mul_f32_e32 v141, 0x3d372713, v139
	v_mul_f32_e32 v140, v138, v140
	v_mul_f32_e32 v141, v139, v141
	v_fma_f32 v140, v138, v140, v138
	v_fma_f32 v141, v139, v141, v139
	v_mul_f32_e32 v144, 0x3d372713, v142
	v_mul_f32_e32 v145, 0x3d372713, v143
	v_mul_f32_e32 v140, 0x3fcc422a, v140
	v_mul_f32_e32 v141, 0x3fcc422a, v141
	v_mul_f32_e32 v144, v142, v144
	v_mul_f32_e32 v145, v143, v145
	v_mul_f32_e32 v140, 0xbfb8aa3b, v140
	v_mul_f32_e32 v141, 0xbfb8aa3b, v141
	v_fma_f32 v144, v142, v144, v142
	v_fma_f32 v145, v143, v145, v143
	v_exp_f32_e32 v140, v140
	v_exp_f32_e32 v141, v141
	v_mul_f32_e32 v144, 0x3fcc422a, v144
	v_mul_f32_e32 v145, 0x3fcc422a, v145
	v_mul_f32_e32 v144, 0xbfb8aa3b, v144
	v_mul_f32_e32 v145, 0xbfb8aa3b, v145
	v_exp_f32_e32 v144, v144
	v_exp_f32_e32 v145, v145
	v_add_f32_e32 v140, 1.0, v140
	v_add_f32_e32 v141, 1.0, v141
	v_rcp_f32_e32 v140, v140
	v_rcp_f32_e32 v141, v141
	v_add_f32_e32 v144, 1.0, v144
	v_add_f32_e32 v145, 1.0, v145
	v_rcp_f32_e32 v144, v144
	v_rcp_f32_e32 v145, v145
	v_pk_mul_f32 v[138:139], v[138:139], v[140:141]
	v_pk_mul_f32 v[142:143], v[142:143], v[144:145]
	v_add_f32_e32 v140, 0, v138
	v_add_f32_e32 v166, v139, v140
	v_add_f32_e32 v144, v142, v166
	v_add_f32_e32 v168, v143, v144
	v_pk_mul_f32 v[144:145], v[10:11], v[132:133] op_sel:[0,1]
	v_mul_f32_e32 v140, v139, v139
	v_mul_f32_e32 v166, 0x3d372713, v144
	v_mul_f32_e32 v167, 0x3d372713, v145
	v_mul_f32_e32 v166, v144, v166
	v_mul_f32_e32 v167, v145, v167
	v_fma_f32 v166, v144, v166, v144
	v_fma_f32 v167, v145, v167, v145
	v_mul_f32_e32 v166, 0x3fcc422a, v166
	v_mul_f32_e32 v167, 0x3fcc422a, v167
	v_mul_f32_e32 v166, 0xbfb8aa3b, v166
	v_mul_f32_e32 v167, 0xbfb8aa3b, v167
	v_exp_f32_e32 v166, v166
	v_exp_f32_e32 v167, v167
	v_pk_fma_f32 v[140:141], v[138:139], v[138:139], v[140:141] op_sel_hi:[1,1,0]
	v_cvt_pk_bf16_f32 v138, v138, v139
	v_add_f32_e32 v166, 1.0, v166
	v_add_f32_e32 v167, 1.0, v167
	v_rcp_f32_e32 v166, v166
	v_rcp_f32_e32 v167, v167
	v_pk_fma_f32 v[140:141], v[142:143], v[142:143], v[140:141]
	v_cvt_pk_bf16_f32 v139, v142, v143
	v_pk_mul_f32 v[144:145], v[144:145], v[166:167]
	s_nop 0
	v_add_f32_e32 v169, v144, v168
	v_mul_f32_e32 v168, v143, v143
	v_mov_b32_e32 v166, v144
	v_mov_b32_e32 v167, v143
	v_pk_add_f32 v[140:141], v[168:169], v[140:141] op_sel_hi:[0,1]
	v_pk_fma_f32 v[140:141], v[166:167], v[166:167], v[140:141]
; __device__ __forceinline__ float sigm(float x) { return __builtin_amdgcn_rcpf(1.f + __expf(-x)); }
; __device__ __forceinline__ float gelu_tanh(float x) { return x * sigm(1.5957691216f * (x + 0.044715f * x * x * x)); }
; __device__ __forceinline__ u32x4 pack8(const float* v) { u32x4 w; w.x = cvtpk(v[0], v[1]); w.y = cvtpk(v[2], v[3]); w.z = cvtpk(v[4], v[5]); w.w = cvtpk(v[6], v[7]); return w; }
;     template <int KIND>
;     __device__ __forceinline__ void act_tile(const pg8::f32x4 (&acc)[2][2][4][2], const float (&rs)[2][4], unsigned char* w_, int row0, int colt, int statslot, int fq_) const {
;     ...
;         for (int ai = 0; ai < 2; ++ai)
; #pragma unroll
;             for (int m = 0; m < 4; ++m) {
;                 const int row = row0 + ai * 128 + m * 16;
;                 float s1 = 0.f, s2 = 0.f;
; #pragma unroll
;                 for (int bj = 0; bj < 2; ++bj) {
;                     float v[8];
; #pragma unroll
;                     for (int n = 0; n < 2; ++n)
; #pragma unroll
;                         for (int j = 0; j < 4; ++j) {
;                             const float a = acc[ai][bj][m][n][j] * rs[ai][m];
;                             const float r = KIND == 2 ? sigm(a) : gelu_tanh(a);
;                             v[n * 4 + j] = r;
;                             if (KIND == 1) { s1 += r; s2 += r * r; }
;                         }
;                     *(u32x4*)(base + (size_t)row * ldc + colt + bj * 128) = pack8(v);
;                 }
;                 if (KIND == 1) {
;                     s1 += __shfl_xor(s1, 16); s1 += __shfl_xor(s1, 32); s2 += __shfl_xor(s2, 16); s2 += __shfl_xor(s2, 32);
;                     if (fq_ == 0) { float* sp = (float*)(w_ + WS_VSTAT) + ((size_t)row * 16 + statslot) * 2; sp[0] = s1; sp[1] = s2; }
;                 }
	v_pk_mul_f32 v[166:167], v[12:13], v[132:133] op_sel:[0,1]
	v_add_f32_e32 v170, v145, v169
	v_mul_f32_e32 v168, 0x3d372713, v166
	v_mul_f32_e32 v169, 0x3d372713, v167
	v_mul_f32_e32 v168, v166, v168
	v_mul_f32_e32 v169, v167, v169
	v_fma_f32 v168, v166, v168, v166
	v_fma_f32 v169, v167, v169, v167
	v_mul_f32_e32 v168, 0x3fcc422a, v168
	v_mul_f32_e32 v169, 0x3fcc422a, v169
	v_mul_f32_e32 v168, 0xbfb8aa3b, v168
	v_mul_f32_e32 v169, 0xbfb8aa3b, v169
	v_exp_f32_e32 v168, v168
	v_exp_f32_e32 v169, v169
	v_add_f32_e32 v168, 1.0, v168
	v_add_f32_e32 v169, 1.0, v169
	v_rcp_f32_e32 v168, v168
	v_rcp_f32_e32 v169, v169
	s_nop 0
	v_pk_mul_f32 v[166:167], v[166:167], v[168:169]
	s_nop 0
	v_add_f32_e32 v171, v166, v170
	v_mul_f32_e32 v170, v145, v145
	v_mov_b32_e32 v168, v166
	v_mov_b32_e32 v169, v145
	v_pk_add_f32 v[140:141], v[170:171], v[140:141] op_sel_hi:[0,1]
	v_pk_fma_f32 v[168:169], v[168:169], v[168:169], v[140:141]
	v_cvt_pk_bf16_f32 v140, v144, v145
	v_cvt_pk_bf16_f32 v141, v166, v167
	global_store_dwordx4 v[134:135], v[138:141], off
	v_add_f32_e32 v170, v167, v171
	s_nop 0
	v_pk_mul_f32 v[138:139], v[6:7], v[132:133] op_sel:[0,1]
	s_nop 0
	v_mul_f32_e32 v140, 0x3d372713, v138
	v_mul_f32_e32 v141, 0x3d372713, v139
	v_mul_f32_e32 v140, v138, v140
	v_mul_f32_e32 v141, v139, v141
	v_fma_f32 v140, v138, v140, v138
	v_fma_f32 v141, v139, v141, v139
	v_mul_f32_e32 v140, 0x3fcc422a, v140
	v_mul_f32_e32 v141, 0x3fcc422a, v141
	v_mul_f32_e32 v140, 0xbfb8aa3b, v140
	v_mul_f32_e32 v141, 0xbfb8aa3b, v141
	v_exp_f32_e32 v140, v140
	v_exp_f32_e32 v141, v141
	v_add_f32_e32 v140, 1.0, v140
	v_add_f32_e32 v141, 1.0, v141
	v_rcp_f32_e32 v140, v140
	v_rcp_f32_e32 v141, v141
	s_nop 0
	v_pk_mul_f32 v[138:139], v[138:139], v[140:141]
	v_mul_f32_e32 v140, v167, v167
	v_add_f32_e32 v142, v138, v170
	v_mov_b32_e32 v166, v138
	v_pk_add_f32 v[140:141], v[140:141], v[168:169] op_sel_hi:[0,1]
	v_pk_fma_f32 v[140:141], v[166:167], v[166:167], v[140:141]
	v_add_f32_e32 v166, v139, v142
	v_pk_mul_f32 v[142:143], v[8:9], v[132:133] op_sel:[0,1]
	v_cvt_pk_bf16_f32 v138, v138, v139
	v_mul_f32_e32 v144, 0x3d372713, v142
	v_mul_f32_e32 v145, 0x3d372713, v143
	v_mul_f32_e32 v144, v142, v144
	v_mul_f32_e32 v145, v143, v145
	v_fma_f32 v144, v142, v144, v142
	v_fma_f32 v145, v143, v145, v143
	v_mul_f32_e32 v144, 0x3fcc422a, v144
	v_mul_f32_e32 v145, 0x3fcc422a, v145
	v_mul_f32_e32 v144, 0xbfb8aa3b, v144
	v_mul_f32_e32 v145, 0xbfb8aa3b, v145
	v_exp_f32_e32 v144, v144
	v_exp_f32_e32 v145, v145
	v_add_f32_e32 v144, 1.0, v144
	v_add_f32_e32 v145, 1.0, v145
	v_rcp_f32_e32 v144, v144
	v_rcp_f32_e32 v145, v145
	s_nop 0
	v_pk_mul_f32 v[142:143], v[142:143], v[144:145]
	s_nop 0
	v_add_f32_e32 v167, v142, v166
	v_mul_f32_e32 v166, v139, v139
	v_mov_b32_e32 v144, v142
	v_mov_b32_e32 v145, v139
	v_pk_add_f32 v[140:141], v[166:167], v[140:141] op_sel_hi:[0,1]
	v_pk_fma_f32 v[140:141], v[144:145], v[144:145], v[140:141]
	v_pk_mul_f32 v[144:145], v[2:3], v[132:133] op_sel:[0,1]
	v_add_f32_e32 v168, v143, v167
	v_mul_f32_e32 v166, 0x3d372713, v144
	v_mul_f32_e32 v167, 0x3d372713, v145
	v_mul_f32_e32 v166, v144, v166
	v_mul_f32_e32 v167, v145, v167
	v_fma_f32 v166, v144, v166, v144
	v_fma_f32 v167, v145, v167, v145
	v_mul_f32_e32 v166, 0x3fcc422a, v166
	v_mul_f32_e32 v167, 0x3fcc422a, v167
	v_mul_f32_e32 v166, 0xbfb8aa3b, v166
	v_mul_f32_e32 v167, 0xbfb8aa3b, v167
	v_exp_f32_e32 v166, v166
	v_exp_f32_e32 v167, v167
	v_cvt_pk_bf16_f32 v139, v142, v143
	v_add_f32_e32 v166, 1.0, v166
	v_add_f32_e32 v167, 1.0, v167
	v_rcp_f32_e32 v166, v166
	v_rcp_f32_e32 v167, v167
	s_nop 0
	v_pk_mul_f32 v[144:145], v[144:145], v[166:167]
	s_nop 0
	v_add_f32_e32 v169, v144, v168
	v_mul_f32_e32 v168, v143, v143
	v_mov_b32_e32 v166, v144
	v_mov_b32_e32 v167, v143
	v_pk_add_f32 v[140:141], v[168:169], v[140:141] op_sel_hi:[0,1]
	v_pk_mul_f32 v[142:143], v[4:5], v[132:133] op_sel:[0,1]
	v_pk_fma_f32 v[166:167], v[166:167], v[166:167], v[140:141]
	v_mul_f32_e32 v141, 0x3d372713, v142
	v_mul_f32_e32 v141, v142, v141
	v_fma_f32 v141, v142, v141, v142
	v_mul_f32_e32 v141, 0x3fcc422a, v141
	v_mul_f32_e32 v141, 0xbfb8aa3b, v141
	v_exp_f32_e32 v141, v141
	v_mul_f32_e32 v174, v145, v145
	v_add_f32_e32 v168, v145, v169
	v_cvt_pk_bf16_f32 v140, v144, v145
	v_add_f32_e32 v141, 1.0, v141
	v_rcp_f32_e32 v170, v141
	v_mul_f32_e32 v141, 0x3d372713, v143
	v_mul_f32_e32 v141, v143, v141
	v_fma_f32 v141, v143, v141, v143
	v_mul_f32_e32 v141, 0x3fcc422a, v141
	v_mul_f32_e32 v141, 0xbfb8aa3b, v141
	v_exp_f32_e32 v141, v141
	v_pk_add_f32 v[166:167], v[174:175], v[166:167] op_sel_hi:[0,1]
	v_add_f32_e32 v141, 1.0, v141
	v_rcp_f32_e32 v171, v141
	s_nop 0
	v_pk_mul_f32 v[172:173], v[142:143], v[170:171]
	s_nop 0
	v_mov_b32_e32 v144, v172
	v_mov_b32_e32 v169, v173
	v_pk_fma_f32 v[144:145], v[144:145], v[144:145], v[166:167]
	v_pk_fma_f32 v[142:143], v[142:143], v[170:171], v[168:169]
	v_pk_mul_f32 v[166:167], v[172:173], v[172:173]
	v_pk_mov_b32 v[144:145], v[172:173], v[144:145] op_sel:[1,0]
	v_mov_b32_e32 v143, v167
	v_pk_add_f32 v[142:143], v[142:143], v[144:145]
	v_cvt_pk_bf16_f32 v141, v172, v173
	global_store_dwordx4 v[134:135], v[138:141], off offset:256
	v_mov_b32_e32 v134, v142
	s_nop 1
	v_permlane16_swap_b32_e32 v134, v142
	v_mov_b32_e32 v135, v143
	s_nop 1
	v_permlane16_swap_b32_e32 v135, v143
	s_waitcnt lgkmcnt(0)
	v_pk_add_f32 v[134:135], v[142:143], v[134:135]
	ds_bpermute_b32 v138, v0, v134
	ds_bpermute_b32 v139, v0, v135
	s_and_saveexec_b64 s[10:11], vcc
	s_cbranch_execz .LBB0_888
	v_lshlrev_b64 v[136:137], 7, v[136:137]
	v_lshl_add_u64 v[136:137], s[0:1], 0, v[136:137]
	s_waitcnt lgkmcnt(0)
	v_pk_add_f32 v[134:135], v[134:135], v[138:139]
	global_store_dwordx2 v[136:137], v[134:135], off

;     __device__ __forceinline__ void operator()(const pg8::f32x4 (&acc)[2][2][4][2], const pg8::Unit& u, int wr, int wc, int fr, int fq) const {
;     ...
;                     ss += (a.x * a.x + a.y * a.y) + (a.z * a.z + a.w * a.w) + (b.x * b.x + b.y * b.y) + (b.z * b.z + b.w * b.w);
;                 }
;                 ss += __shfl_xor(ss, 16); ss += __shfl_xor(ss, 32);
;                 if (fq_ == 0) xch[(ai * 128 + wr * 64 + m * 16 + fr_) * 4 + wc] = ss;
.LBB0_1286:
	v_mul_f32_e32 v110, v110, v110
	v_mul_f32_e32 v102, v102, v102
	v_fmac_f32_e32 v110, v111, v111
	v_mul_f32_e32 v111, v113, v113
	v_fmac_f32_e32 v102, v103, v103
	v_mul_f32_e32 v103, v105, v105
	v_fmac_f32_e32 v111, v112, v112
	v_mul_f32_e32 v106, v106, v106
	v_fmac_f32_e32 v103, v104, v104
	v_mul_f32_e32 v98, v98, v98
	v_add_f32_e32 v110, v111, v110
	v_fmac_f32_e32 v106, v107, v107
	v_mul_f32_e32 v107, v108, v108
	v_add_f32_e32 v102, v103, v102
	v_fmac_f32_e32 v98, v99, v99
	v_mul_f32_e32 v99, v100, v100
	v_add_f32_e32 v106, v106, v110
	v_fmac_f32_e32 v107, v109, v109
	v_add_f32_e32 v98, v98, v102
	v_fmac_f32_e32 v99, v101, v101
	v_add_f32_e32 v106, v107, v106
	v_add_f32_e32 v98, v99, v98
	v_add_f32_e32 v98, v106, v98
	v_mov_b32_e32 v99, v98
	s_nop 1
	v_permlane16_swap_b32_e32 v99, v98
	s_waitcnt lgkmcnt(0)
	v_add_f32_e32 v98, v98, v99
	v_mov_b32_e32 v99, v98
	s_nop 1
	v_permlane32_swap_b32_e32 v99, v98
	s_and_saveexec_b64 s[30:31], s[10:11]
	s_cbranch_execz .LBB0_1288
	s_waitcnt lgkmcnt(0)
	v_add_f32_e32 v98, v98, v99
	ds_write_b32 v147, v98 offset:256

;     __device__ __forceinline__ void operator()(const pg8::f32x4 (&acc)[2][2][4][2], const pg8::Unit& u, int wr, int wc, int fr, int fq) const {
;     ...
;                     ss += (a.x * a.x + a.y * a.y) + (a.z * a.z + a.w * a.w) + (b.x * b.x + b.y * b.y) + (b.z * b.z + b.w * b.w);
;                 }
;                 ss += __shfl_xor(ss, 16); ss += __shfl_xor(ss, 32);
;                 if (fq_ == 0) xch[(ai * 128 + wr * 64 + m * 16 + fr_) * 4 + wc] = ss;
.LBB0_1296:
	v_mul_f32_e32 v94, v94, v94
	v_mul_f32_e32 v86, v86, v86
	v_fmac_f32_e32 v94, v95, v95
	v_mul_f32_e32 v95, v97, v97
	v_fmac_f32_e32 v86, v87, v87
	v_mul_f32_e32 v87, v89, v89
	v_fmac_f32_e32 v95, v96, v96
	v_mul_f32_e32 v90, v90, v90
	v_fmac_f32_e32 v87, v88, v88
	v_mul_f32_e32 v82, v82, v82
	v_add_f32_e32 v94, v95, v94
	v_fmac_f32_e32 v90, v91, v91
	v_mul_f32_e32 v91, v92, v92
	v_add_f32_e32 v86, v87, v86
	v_fmac_f32_e32 v82, v83, v83
	v_mul_f32_e32 v83, v84, v84
	v_add_f32_e32 v90, v90, v94
	v_fmac_f32_e32 v91, v93, v93
	v_add_f32_e32 v82, v82, v86
	v_fmac_f32_e32 v83, v85, v85
	v_add_f32_e32 v90, v91, v90
	v_add_f32_e32 v82, v83, v82
	v_add_f32_e32 v82, v90, v82
	v_mov_b32_e32 v83, v82
	s_nop 1
	v_permlane16_swap_b32_e32 v83, v82
	s_waitcnt lgkmcnt(0)
	v_add_f32_e32 v82, v82, v83
	v_mov_b32_e32 v83, v82
	s_nop 1
	v_permlane32_swap_b32_e32 v83, v82
	s_and_saveexec_b64 s[30:31], s[10:11]
	s_cbranch_execz .LBB0_1298
	s_waitcnt lgkmcnt(0)
	v_add_f32_e32 v82, v82, v83
	ds_write_b32 v147, v82 offset:512

;     __device__ __forceinline__ void operator()(const pg8::f32x4 (&acc)[2][2][4][2], const pg8::Unit& u, int wr, int wc, int fr, int fq) const {
;     ...
;                     ss += (a.x * a.x + a.y * a.y) + (a.z * a.z + a.w * a.w) + (b.x * b.x + b.y * b.y) + (b.z * b.z + b.w * b.w);
;                 }
;                 ss += __shfl_xor(ss, 16); ss += __shfl_xor(ss, 32);
;                 if (fq_ == 0) xch[(ai * 128 + wr * 64 + m * 16 + fr_) * 4 + wc] = ss;
.LBB0_1306:
	v_mul_f32_e32 v78, v78, v78
	v_mul_f32_e32 v70, v70, v70
	v_fmac_f32_e32 v78, v79, v79
	v_mul_f32_e32 v79, v81, v81
	v_fmac_f32_e32 v70, v71, v71
	v_mul_f32_e32 v71, v73, v73
	v_fmac_f32_e32 v79, v80, v80
	v_mul_f32_e32 v74, v74, v74
	v_fmac_f32_e32 v71, v72, v72
	v_mul_f32_e32 v66, v66, v66
	v_add_f32_e32 v78, v79, v78
	v_fmac_f32_e32 v74, v75, v75
	v_mul_f32_e32 v75, v76, v76
	v_add_f32_e32 v70, v71, v70
	v_fmac_f32_e32 v66, v67, v67
	v_mul_f32_e32 v67, v68, v68
	v_add_f32_e32 v74, v74, v78
	v_fmac_f32_e32 v75, v77, v77
	v_add_f32_e32 v66, v66, v70
	v_fmac_f32_e32 v67, v69, v69
	v_add_f32_e32 v74, v75, v74
	v_add_f32_e32 v66, v67, v66
	v_add_f32_e32 v66, v74, v66
	v_mov_b32_e32 v67, v66
	s_nop 1
	v_permlane16_swap_b32_e32 v67, v66
	s_waitcnt lgkmcnt(0)
	v_add_f32_e32 v66, v66, v67
	v_mov_b32_e32 v67, v66
	s_nop 1
	v_permlane32_swap_b32_e32 v67, v66
	s_and_saveexec_b64 s[30:31], s[10:11]
	s_cbranch_execz .LBB0_1308
	s_waitcnt lgkmcnt(0)
	v_add_f32_e32 v66, v66, v67
	ds_write_b32 v147, v66 offset:768

;     __device__ __forceinline__ void operator()(const pg8::f32x4 (&acc)[2][2][4][2], const pg8::Unit& u, int wr, int wc, int fr, int fq) const {
;     ...
;                     ss += (a.x * a.x + a.y * a.y) + (a.z * a.z + a.w * a.w) + (b.x * b.x + b.y * b.y) + (b.z * b.z + b.w * b.w);
;                 }
;                 ss += __shfl_xor(ss, 16); ss += __shfl_xor(ss, 32);
;                 if (fq_ == 0) xch[(ai * 128 + wr * 64 + m * 16 + fr_) * 4 + wc] = ss;
.LBB0_1316:
	v_mul_f32_e32 v62, v62, v62
	v_mul_f32_e32 v54, v54, v54
	v_fmac_f32_e32 v62, v63, v63
	v_mul_f32_e32 v63, v65, v65
	v_fmac_f32_e32 v54, v55, v55
	v_mul_f32_e32 v55, v57, v57
	v_fmac_f32_e32 v63, v64, v64
	v_mul_f32_e32 v58, v58, v58
	v_fmac_f32_e32 v55, v56, v56
	v_mul_f32_e32 v50, v50, v50
	v_add_f32_e32 v62, v63, v62
	v_fmac_f32_e32 v58, v59, v59
	v_mul_f32_e32 v59, v60, v60
	v_add_f32_e32 v54, v55, v54
	v_fmac_f32_e32 v50, v51, v51
	v_mul_f32_e32 v51, v52, v52
	v_add_f32_e32 v58, v58, v62
	v_fmac_f32_e32 v59, v61, v61
	v_add_f32_e32 v50, v50, v54
	v_fmac_f32_e32 v51, v53, v53
	v_add_f32_e32 v58, v59, v58
	v_add_f32_e32 v50, v51, v50
	v_add_f32_e32 v50, v58, v50
	v_mov_b32_e32 v51, v50
	s_nop 1
	v_permlane16_swap_b32_e32 v51, v50
	s_waitcnt lgkmcnt(0)
	v_add_f32_e32 v50, v50, v51
	v_mov_b32_e32 v51, v50
	s_nop 1
	v_permlane32_swap_b32_e32 v51, v50
	s_and_saveexec_b64 s[30:31], s[10:11]
	s_cbranch_execz .LBB0_1318
	s_waitcnt lgkmcnt(0)
	v_add_f32_e32 v50, v50, v51
	ds_write_b32 v147, v50 offset:2048

;     __device__ __forceinline__ void operator()(const pg8::f32x4 (&acc)[2][2][4][2], const pg8::Unit& u, int wr, int wc, int fr, int fq) const {
;     ...
;                     ss += (a.x * a.x + a.y * a.y) + (a.z * a.z + a.w * a.w) + (b.x * b.x + b.y * b.y) + (b.z * b.z + b.w * b.w);
;                 }
;                 ss += __shfl_xor(ss, 16); ss += __shfl_xor(ss, 32);
;                 if (fq_ == 0) xch[(ai * 128 + wr * 64 + m * 16 + fr_) * 4 + wc] = ss;
.LBB0_1326:
	v_mul_f32_e32 v46, v46, v46
	v_mul_f32_e32 v38, v38, v38
	v_fmac_f32_e32 v46, v47, v47
	v_mul_f32_e32 v47, v49, v49
	v_fmac_f32_e32 v38, v39, v39
	v_mul_f32_e32 v39, v41, v41
	v_fmac_f32_e32 v47, v48, v48
	v_mul_f32_e32 v42, v42, v42
	v_fmac_f32_e32 v39, v40, v40
	v_mul_f32_e32 v34, v34, v34
	v_add_f32_e32 v46, v47, v46
	v_fmac_f32_e32 v42, v43, v43
	v_mul_f32_e32 v43, v44, v44
	v_add_f32_e32 v38, v39, v38
	v_fmac_f32_e32 v34, v35, v35
	v_mul_f32_e32 v35, v36, v36
	v_add_f32_e32 v42, v42, v46
	v_fmac_f32_e32 v43, v45, v45
	v_add_f32_e32 v34, v34, v38
	v_fmac_f32_e32 v35, v37, v37
	v_add_f32_e32 v42, v43, v42
	v_add_f32_e32 v34, v35, v34
	v_add_f32_e32 v34, v42, v34
	v_mov_b32_e32 v35, v34
	s_nop 1
	v_permlane16_swap_b32_e32 v35, v34
	s_waitcnt lgkmcnt(0)
	v_add_f32_e32 v34, v34, v35
	v_mov_b32_e32 v35, v34
	s_nop 1
	v_permlane32_swap_b32_e32 v35, v34
	s_and_saveexec_b64 s[30:31], s[10:11]
	s_cbranch_execz .LBB0_1328
	s_waitcnt lgkmcnt(0)
	v_add_f32_e32 v34, v34, v35
	ds_write_b32 v147, v34 offset:2304

;     __device__ __forceinline__ void operator()(const pg8::f32x4 (&acc)[2][2][4][2], const pg8::Unit& u, int wr, int wc, int fr, int fq) const {
;     ...
;                     ss += (a.x * a.x + a.y * a.y) + (a.z * a.z + a.w * a.w) + (b.x * b.x + b.y * b.y) + (b.z * b.z + b.w * b.w);
;                 }
;                 ss += __shfl_xor(ss, 16); ss += __shfl_xor(ss, 32);
;                 if (fq_ == 0) xch[(ai * 128 + wr * 64 + m * 16 + fr_) * 4 + wc] = ss;
.LBB0_1336:
	v_mul_f32_e32 v30, v30, v30
	v_mul_f32_e32 v22, v22, v22
	v_fmac_f32_e32 v30, v31, v31
	v_mul_f32_e32 v31, v33, v33
	v_fmac_f32_e32 v22, v23, v23
	v_mul_f32_e32 v23, v25, v25
	v_fmac_f32_e32 v31, v32, v32
	v_mul_f32_e32 v26, v26, v26
	v_fmac_f32_e32 v23, v24, v24
	v_mul_f32_e32 v18, v18, v18
	v_add_f32_e32 v30, v31, v30
	v_fmac_f32_e32 v26, v27, v27
	v_mul_f32_e32 v27, v28, v28
	v_add_f32_e32 v22, v23, v22
	v_fmac_f32_e32 v18, v19, v19
	v_mul_f32_e32 v19, v20, v20
	v_add_f32_e32 v26, v26, v30
	v_fmac_f32_e32 v27, v29, v29
	v_add_f32_e32 v18, v18, v22
	v_fmac_f32_e32 v19, v21, v21
	v_add_f32_e32 v26, v27, v26
	v_add_f32_e32 v18, v19, v18
	v_add_f32_e32 v18, v26, v18
	v_mov_b32_e32 v19, v18
	s_nop 1
	v_permlane16_swap_b32_e32 v19, v18
	s_waitcnt lgkmcnt(0)
	v_add_f32_e32 v18, v18, v19
	v_mov_b32_e32 v19, v18
	s_nop 1
	v_permlane32_swap_b32_e32 v19, v18
	s_and_saveexec_b64 s[26:27], s[10:11]
	s_cbranch_execz .LBB0_1338
	s_waitcnt lgkmcnt(0)
	v_add_f32_e32 v18, v18, v19
	ds_write_b32 v147, v18 offset:2560

;     __device__ __forceinline__ void operator()(const pg8::f32x4 (&acc)[2][2][4][2], const pg8::Unit& u, int wr, int wc, int fr, int fq) const {
;     ...
;                     ss += (a.x * a.x + a.y * a.y) + (a.z * a.z + a.w * a.w) + (b.x * b.x + b.y * b.y) + (b.z * b.z + b.w * b.w);
;                 }
;                 ss += __shfl_xor(ss, 16); ss += __shfl_xor(ss, 32);
;                 if (fq_ == 0) xch[(ai * 128 + wr * 64 + m * 16 + fr_) * 4 + wc] = ss;
.LBB0_1346:
	v_mul_f32_e32 v14, v14, v14
	v_mul_f32_e32 v6, v6, v6
	v_fmac_f32_e32 v14, v15, v15
	v_mul_f32_e32 v15, v17, v17
	v_fmac_f32_e32 v6, v7, v7
	v_mul_f32_e32 v7, v9, v9
	v_fmac_f32_e32 v15, v16, v16
	v_mul_f32_e32 v10, v10, v10
	v_fmac_f32_e32 v7, v8, v8
	v_mul_f32_e32 v2, v2, v2
	v_add_f32_e32 v14, v15, v14
	v_fmac_f32_e32 v10, v11, v11
	v_mul_f32_e32 v11, v12, v12
	v_add_f32_e32 v6, v7, v6
	v_fmac_f32_e32 v2, v3, v3
	v_mul_f32_e32 v3, v4, v4
	v_add_f32_e32 v10, v10, v14
	v_fmac_f32_e32 v11, v13, v13
	v_add_f32_e32 v2, v2, v6
	v_fmac_f32_e32 v3, v5, v5
	v_add_f32_e32 v10, v11, v10
	v_add_f32_e32 v2, v3, v2
	v_add_f32_e32 v2, v10, v2
	v_mov_b32_e32 v3, v2
	s_nop 1
	v_permlane16_swap_b32_e32 v3, v2
	s_waitcnt lgkmcnt(0)
	v_add_f32_e32 v2, v2, v3
	v_mov_b32_e32 v3, v2
	s_nop 1
	v_permlane32_swap_b32_e32 v3, v2
	s_and_saveexec_b64 s[24:25], s[10:11]
	s_cbranch_execz .LBB0_1348
	s_waitcnt lgkmcnt(0)
	v_add_f32_e32 v2, v2, v3
	ds_write_b32 v147, v2 offset:2816
